# v52 + GEMM K-loops (bf16): B1 fragment ds_reads issued last in the load segment, barrier waits only lgkmcnt(4), lgkmcnt(0) moved to mid MFMA block (first consumer of B1)
# baseline (speedup 1.0000x reference)
.LBB0_422:
	ds_read_b128 v[146:149], v154
	ds_read_b128 v[158:161], v154 offset:1024
	ds_read_b128 v[162:165], v154 offset:2048
	ds_read_b128 v[166:169], v154 offset:3072
	s_add_u32 s30, s28, 0xfc000
	s_addc_u32 s31, s29, 0
	s_cmp_eq_u32 s53, 60
	s_cselect_b32 s36, s21, s30
	s_cselect_b32 s37, s9, s31
	s_cselect_b32 s34, s50, s51
	s_cselect_b32 s35, s19, s52
	s_add_u32 s30, s36, 0x100000
	s_addc_u32 s31, s37, 0
	s_add_i32 m0, s1, 0xc000
	ds_read_b128 v[190:193], v156
	ds_read_b128 v[194:197], v156 offset:1024
	ds_read_b128 v[198:201], v156 offset:2048
	ds_read_b128 v[202:205], v156 offset:3072
	ds_read_b128 v[206:209], v156 offset:4096
	ds_read_b128 v[210:213], v156 offset:5120
	ds_read_b128 v[214:217], v156 offset:6144
	ds_read_b128 v[218:221], v156 offset:7168
	global_load_lds_dwordx4 v138, s[28:29]
	s_add_i32 m0, s1, 0xe000
	s_nop 0
	global_load_lds_dwordx4 v140, s[28:29]
	ds_read_b128 v[170:173], v155
	ds_read_b128 v[178:181], v155 offset:1024
	ds_read_b128 v[182:185], v155 offset:2048
	ds_read_b128 v[186:189], v155 offset:3072
	s_waitcnt vmcnt(8)
	s_waitcnt lgkmcnt(4)
	s_setprio 1
	s_barrier
	v_mfma_f32_16x16x32_bf16 v[126:129], v[146:149], v[190:193], v[126:129]
	v_mfma_f32_16x16x32_bf16 v[126:129], v[158:161], v[194:197], v[126:129]
	v_mfma_f32_16x16x32_bf16 v[110:113], v[146:149], v[198:201], v[110:113]
	v_mfma_f32_16x16x32_bf16 v[110:113], v[158:161], v[202:205], v[110:113]
	v_mfma_f32_16x16x32_bf16 v[94:97], v[146:149], v[206:209], v[94:97]
	v_mfma_f32_16x16x32_bf16 v[94:97], v[158:161], v[210:213], v[94:97]
	v_mfma_f32_16x16x32_bf16 v[78:81], v[146:149], v[214:217], v[78:81]
	v_mfma_f32_16x16x32_bf16 v[78:81], v[158:161], v[218:221], v[78:81]
	v_mfma_f32_16x16x32_bf16 v[122:125], v[162:165], v[190:193], v[122:125]
	v_mfma_f32_16x16x32_bf16 v[122:125], v[166:169], v[194:197], v[122:125]
	v_mfma_f32_16x16x32_bf16 v[106:109], v[162:165], v[198:201], v[106:109]
	v_mfma_f32_16x16x32_bf16 v[106:109], v[166:169], v[202:205], v[106:109]
	v_mfma_f32_16x16x32_bf16 v[90:93], v[162:165], v[206:209], v[90:93]
	v_mfma_f32_16x16x32_bf16 v[90:93], v[166:169], v[210:213], v[90:93]
	v_mfma_f32_16x16x32_bf16 v[74:77], v[162:165], v[214:217], v[74:77]
	v_mfma_f32_16x16x32_bf16 v[74:77], v[166:169], v[218:221], v[74:77]
	s_setprio 0
	s_waitcnt lgkmcnt(0)
	s_setprio 1
	v_mfma_f32_16x16x32_bf16 v[118:121], v[170:173], v[190:193], v[118:121]
	v_mfma_f32_16x16x32_bf16 v[118:121], v[178:181], v[194:197], v[118:121]
	v_mfma_f32_16x16x32_bf16 v[102:105], v[170:173], v[198:201], v[102:105]
	v_mfma_f32_16x16x32_bf16 v[102:105], v[178:181], v[202:205], v[102:105]
	v_mfma_f32_16x16x32_bf16 v[86:89], v[170:173], v[206:209], v[86:89]
	v_mfma_f32_16x16x32_bf16 v[86:89], v[178:181], v[210:213], v[86:89]
	v_mfma_f32_16x16x32_bf16 v[70:73], v[170:173], v[214:217], v[70:73]
	v_mfma_f32_16x16x32_bf16 v[70:73], v[178:181], v[218:221], v[70:73]
	v_mfma_f32_16x16x32_bf16 v[114:117], v[182:185], v[190:193], v[114:117]
	v_mfma_f32_16x16x32_bf16 v[114:117], v[186:189], v[194:197], v[114:117]
	v_mfma_f32_16x16x32_bf16 v[98:101], v[182:185], v[198:201], v[98:101]
	v_mfma_f32_16x16x32_bf16 v[98:101], v[186:189], v[202:205], v[98:101]
	v_mfma_f32_16x16x32_bf16 v[82:85], v[182:185], v[206:209], v[82:85]
	v_mfma_f32_16x16x32_bf16 v[82:85], v[186:189], v[210:213], v[82:85]
	v_mfma_f32_16x16x32_bf16 v[66:69], v[182:185], v[214:217], v[66:69]
	v_mfma_f32_16x16x32_bf16 v[66:69], v[186:189], v[218:221], v[66:69]
	s_barrier
	s_setprio 0
	s_add_i32 s54, s48, s0
	s_mov_b32 m0, s54
	ds_read_b128 v[190:193], v156 offset:16384
	ds_read_b128 v[194:197], v156 offset:17408
	ds_read_b128 v[198:201], v156 offset:18432
	ds_read_b128 v[202:205], v156 offset:19456
	ds_read_b128 v[206:209], v156 offset:20480
	ds_read_b128 v[210:213], v156 offset:21504
	ds_read_b128 v[214:217], v156 offset:22528
	ds_read_b128 v[218:221], v156 offset:23552
	global_load_lds_dwordx4 v132, s[34:35]
	s_add_i32 m0, s54, 0x2000
	s_add_u32 s54, s34, 0x4000
	s_addc_u32 s55, s35, 0
	s_add_i32 s56, s49, s0
	global_load_lds_dwordx4 v136, s[34:35]
	s_mov_b32 m0, s56
	s_nop 0
	global_load_lds_dwordx4 v132, s[54:55]
	s_add_i32 m0, s56, 0x2000
	s_nop 0
	global_load_lds_dwordx4 v136, s[54:55]
	s_mov_b32 m0, s1
	s_nop 0
	global_load_lds_dwordx4 v130, s[36:37]
	s_mov_b32 m0, s27
	s_nop 0
	global_load_lds_dwordx4 v134, s[36:37]
	s_waitcnt vmcnt(8)
	s_waitcnt lgkmcnt(0)
	s_setprio 1
	s_barrier
	v_mfma_f32_16x16x32_bf16 v[62:65], v[146:149], v[190:193], v[62:65]
	v_mfma_f32_16x16x32_bf16 v[62:65], v[158:161], v[194:197], v[62:65]
	v_mfma_f32_16x16x32_bf16 v[46:49], v[146:149], v[198:201], v[46:49]
	v_mfma_f32_16x16x32_bf16 v[46:49], v[158:161], v[202:205], v[46:49]
	v_mfma_f32_16x16x32_bf16 v[30:33], v[146:149], v[206:209], v[30:33]
	v_mfma_f32_16x16x32_bf16 v[30:33], v[158:161], v[210:213], v[30:33]
	v_mfma_f32_16x16x32_bf16 v[14:17], v[146:149], v[214:217], v[14:17]
	v_mfma_f32_16x16x32_bf16 v[14:17], v[158:161], v[218:221], v[14:17]
	v_mfma_f32_16x16x32_bf16 v[58:61], v[162:165], v[190:193], v[58:61]
	v_mfma_f32_16x16x32_bf16 v[58:61], v[166:169], v[194:197], v[58:61]
	v_mfma_f32_16x16x32_bf16 v[42:45], v[162:165], v[198:201], v[42:45]
	v_mfma_f32_16x16x32_bf16 v[42:45], v[166:169], v[202:205], v[42:45]
	v_mfma_f32_16x16x32_bf16 v[26:29], v[162:165], v[206:209], v[26:29]
	v_mfma_f32_16x16x32_bf16 v[26:29], v[166:169], v[210:213], v[26:29]
	v_mfma_f32_16x16x32_bf16 v[10:13], v[162:165], v[214:217], v[10:13]
	v_mfma_f32_16x16x32_bf16 v[10:13], v[166:169], v[218:221], v[10:13]
	s_setprio 0
	s_setprio 1
	v_mfma_f32_16x16x32_bf16 v[54:57], v[170:173], v[190:193], v[54:57]
	v_mfma_f32_16x16x32_bf16 v[54:57], v[178:181], v[194:197], v[54:57]
	v_mfma_f32_16x16x32_bf16 v[38:41], v[170:173], v[198:201], v[38:41]
	v_mfma_f32_16x16x32_bf16 v[38:41], v[178:181], v[202:205], v[38:41]
	v_mfma_f32_16x16x32_bf16 v[22:25], v[170:173], v[206:209], v[22:25]
	v_mfma_f32_16x16x32_bf16 v[22:25], v[178:181], v[210:213], v[22:25]
	v_mfma_f32_16x16x32_bf16 v[6:9], v[170:173], v[214:217], v[6:9]
	v_mfma_f32_16x16x32_bf16 v[6:9], v[178:181], v[218:221], v[6:9]
	v_mfma_f32_16x16x32_bf16 v[50:53], v[182:185], v[190:193], v[50:53]
	v_mfma_f32_16x16x32_bf16 v[50:53], v[186:189], v[194:197], v[50:53]
	v_mfma_f32_16x16x32_bf16 v[34:37], v[182:185], v[198:201], v[34:37]
	v_mfma_f32_16x16x32_bf16 v[34:37], v[186:189], v[202:205], v[34:37]
	v_mfma_f32_16x16x32_bf16 v[18:21], v[182:185], v[206:209], v[18:21]
	v_mfma_f32_16x16x32_bf16 v[18:21], v[186:189], v[210:213], v[18:21]
	v_mfma_f32_16x16x32_bf16 v[2:5], v[182:185], v[214:217], v[2:5]
	v_mfma_f32_16x16x32_bf16 v[2:5], v[186:189], v[218:221], v[2:5]
	s_barrier
	s_setprio 0
	s_add_i32 s54, 0, 0x18000
	v_add_u32_e32 v150, s54, v153
	s_add_i32 s55, 0, 0x1c000
	ds_read_b128 v[146:149], v150
	ds_read_b128 v[158:161], v150 offset:1024
	ds_read_b128 v[162:165], v150 offset:2048
	ds_read_b128 v[166:169], v150 offset:3072
	v_add_u32_e32 v150, s55, v153
	s_add_u32 s36, s36, 0x4000
	s_addc_u32 s37, s37, 0
	s_mov_b32 m0, s33
	ds_read_b128 v[190:193], v156 offset:32768
	ds_read_b128 v[194:197], v156 offset:33792
	ds_read_b128 v[198:201], v156 offset:34816
	ds_read_b128 v[202:205], v156 offset:35840
	ds_read_b128 v[206:209], v156 offset:36864
	ds_read_b128 v[210:213], v156 offset:37888
	ds_read_b128 v[214:217], v156 offset:38912
	ds_read_b128 v[218:221], v156 offset:39936
	global_load_lds_dwordx4 v130, s[36:37]
	s_mov_b32 m0, s38
	s_nop 0
	global_load_lds_dwordx4 v134, s[36:37]
	ds_read_b128 v[170:173], v150
	ds_read_b128 v[178:181], v150 offset:1024
	ds_read_b128 v[182:185], v150 offset:2048
	ds_read_b128 v[186:189], v150 offset:3072
	s_waitcnt vmcnt(8)
	s_waitcnt lgkmcnt(4)
	s_setprio 1
	s_barrier
	v_mfma_f32_16x16x32_bf16 v[126:129], v[146:149], v[190:193], v[126:129]
	v_mfma_f32_16x16x32_bf16 v[126:129], v[158:161], v[194:197], v[126:129]
	v_mfma_f32_16x16x32_bf16 v[110:113], v[146:149], v[198:201], v[110:113]
	v_mfma_f32_16x16x32_bf16 v[110:113], v[158:161], v[202:205], v[110:113]
	v_mfma_f32_16x16x32_bf16 v[94:97], v[146:149], v[206:209], v[94:97]
	v_mfma_f32_16x16x32_bf16 v[94:97], v[158:161], v[210:213], v[94:97]
	v_mfma_f32_16x16x32_bf16 v[78:81], v[146:149], v[214:217], v[78:81]
	v_mfma_f32_16x16x32_bf16 v[78:81], v[158:161], v[218:221], v[78:81]
	v_mfma_f32_16x16x32_bf16 v[122:125], v[162:165], v[190:193], v[122:125]
	v_mfma_f32_16x16x32_bf16 v[122:125], v[166:169], v[194:197], v[122:125]
	v_mfma_f32_16x16x32_bf16 v[106:109], v[162:165], v[198:201], v[106:109]
	v_mfma_f32_16x16x32_bf16 v[106:109], v[166:169], v[202:205], v[106:109]
	v_mfma_f32_16x16x32_bf16 v[90:93], v[162:165], v[206:209], v[90:93]
	v_mfma_f32_16x16x32_bf16 v[90:93], v[166:169], v[210:213], v[90:93]
	v_mfma_f32_16x16x32_bf16 v[74:77], v[162:165], v[214:217], v[74:77]
	v_mfma_f32_16x16x32_bf16 v[74:77], v[166:169], v[218:221], v[74:77]
	s_setprio 0
	s_waitcnt lgkmcnt(0)
	s_setprio 1
	v_mfma_f32_16x16x32_bf16 v[118:121], v[170:173], v[190:193], v[118:121]
	v_mfma_f32_16x16x32_bf16 v[118:121], v[178:181], v[194:197], v[118:121]
	v_mfma_f32_16x16x32_bf16 v[102:105], v[170:173], v[198:201], v[102:105]
	v_mfma_f32_16x16x32_bf16 v[102:105], v[178:181], v[202:205], v[102:105]
	v_mfma_f32_16x16x32_bf16 v[86:89], v[170:173], v[206:209], v[86:89]
	v_mfma_f32_16x16x32_bf16 v[86:89], v[178:181], v[210:213], v[86:89]
	v_mfma_f32_16x16x32_bf16 v[70:73], v[170:173], v[214:217], v[70:73]
	v_mfma_f32_16x16x32_bf16 v[70:73], v[178:181], v[218:221], v[70:73]
	v_mfma_f32_16x16x32_bf16 v[114:117], v[182:185], v[190:193], v[114:117]
	v_mfma_f32_16x16x32_bf16 v[114:117], v[186:189], v[194:197], v[114:117]
	v_mfma_f32_16x16x32_bf16 v[98:101], v[182:185], v[198:201], v[98:101]
	v_mfma_f32_16x16x32_bf16 v[98:101], v[186:189], v[202:205], v[98:101]
	v_mfma_f32_16x16x32_bf16 v[82:85], v[182:185], v[206:209], v[82:85]
	v_mfma_f32_16x16x32_bf16 v[82:85], v[186:189], v[210:213], v[82:85]
	v_mfma_f32_16x16x32_bf16 v[66:69], v[182:185], v[214:217], v[66:69]
	v_mfma_f32_16x16x32_bf16 v[66:69], v[186:189], v[218:221], v[66:69]
	s_barrier
	s_setprio 0
	s_add_u32 s36, s34, 0x380000
	s_addc_u32 s37, s35, 0
	s_add_i32 s54, s54, s0
	s_mov_b32 m0, s54
	ds_read_b128 v[190:193], v156 offset:49152
	ds_read_b128 v[194:197], v156 offset:50176
	ds_read_b128 v[198:201], v156 offset:51200
	ds_read_b128 v[202:205], v156 offset:52224
	ds_read_b128 v[206:209], v156 offset:53248
	ds_read_b128 v[210:213], v156 offset:54272
	ds_read_b128 v[214:217], v156 offset:55296
	ds_read_b128 v[218:221], v156 offset:56320
	global_load_lds_dwordx4 v132, s[36:37]
	s_add_i32 m0, s54, 0x2000
	s_add_u32 s34, s34, 0x384000
	s_addc_u32 s35, s35, 0
	global_load_lds_dwordx4 v136, s[36:37]
	s_add_i32 s36, s55, s0
	s_mov_b32 m0, s36
	s_nop 0
	global_load_lds_dwordx4 v132, s[34:35]
	s_add_i32 m0, s36, 0x2000
	s_nop 0
	global_load_lds_dwordx4 v136, s[34:35]
	s_mov_b32 m0, s44
	s_nop 0
	global_load_lds_dwordx4 v130, s[30:31]
	s_mov_b32 m0, s45
	s_nop 0
	global_load_lds_dwordx4 v134, s[30:31]
	s_waitcnt vmcnt(8)
	s_waitcnt lgkmcnt(0)
	s_setprio 1
	s_barrier
	v_mfma_f32_16x16x32_bf16 v[62:65], v[146:149], v[190:193], v[62:65]
	v_mfma_f32_16x16x32_bf16 v[62:65], v[158:161], v[194:197], v[62:65]
	v_mfma_f32_16x16x32_bf16 v[46:49], v[146:149], v[198:201], v[46:49]
	v_mfma_f32_16x16x32_bf16 v[46:49], v[158:161], v[202:205], v[46:49]
	v_mfma_f32_16x16x32_bf16 v[30:33], v[146:149], v[206:209], v[30:33]
	v_mfma_f32_16x16x32_bf16 v[30:33], v[158:161], v[210:213], v[30:33]
	v_mfma_f32_16x16x32_bf16 v[14:17], v[146:149], v[214:217], v[14:17]
	v_mfma_f32_16x16x32_bf16 v[14:17], v[158:161], v[218:221], v[14:17]
	v_mfma_f32_16x16x32_bf16 v[58:61], v[162:165], v[190:193], v[58:61]
	v_mfma_f32_16x16x32_bf16 v[58:61], v[166:169], v[194:197], v[58:61]
	v_mfma_f32_16x16x32_bf16 v[42:45], v[162:165], v[198:201], v[42:45]
	v_mfma_f32_16x16x32_bf16 v[42:45], v[166:169], v[202:205], v[42:45]
	v_mfma_f32_16x16x32_bf16 v[26:29], v[162:165], v[206:209], v[26:29]
	v_mfma_f32_16x16x32_bf16 v[26:29], v[166:169], v[210:213], v[26:29]
	v_mfma_f32_16x16x32_bf16 v[10:13], v[162:165], v[214:217], v[10:13]
	v_mfma_f32_16x16x32_bf16 v[10:13], v[166:169], v[218:221], v[10:13]
	s_setprio 0
	s_setprio 1
	v_mfma_f32_16x16x32_bf16 v[54:57], v[170:173], v[190:193], v[54:57]
	v_mfma_f32_16x16x32_bf16 v[54:57], v[178:181], v[194:197], v[54:57]
	v_mfma_f32_16x16x32_bf16 v[38:41], v[170:173], v[198:201], v[38:41]
	v_mfma_f32_16x16x32_bf16 v[38:41], v[178:181], v[202:205], v[38:41]
	v_mfma_f32_16x16x32_bf16 v[22:25], v[170:173], v[206:209], v[22:25]
	v_mfma_f32_16x16x32_bf16 v[22:25], v[178:181], v[210:213], v[22:25]
	v_mfma_f32_16x16x32_bf16 v[6:9], v[170:173], v[214:217], v[6:9]
	v_mfma_f32_16x16x32_bf16 v[6:9], v[178:181], v[218:221], v[6:9]
	v_mfma_f32_16x16x32_bf16 v[50:53], v[182:185], v[190:193], v[50:53]
	v_mfma_f32_16x16x32_bf16 v[50:53], v[186:189], v[194:197], v[50:53]
	v_mfma_f32_16x16x32_bf16 v[34:37], v[182:185], v[198:201], v[34:37]
	v_mfma_f32_16x16x32_bf16 v[34:37], v[186:189], v[202:205], v[34:37]
	v_mfma_f32_16x16x32_bf16 v[18:21], v[182:185], v[206:209], v[18:21]
	v_mfma_f32_16x16x32_bf16 v[18:21], v[186:189], v[210:213], v[18:21]
	v_mfma_f32_16x16x32_bf16 v[2:5], v[182:185], v[214:217], v[2:5]
	v_mfma_f32_16x16x32_bf16 v[2:5], v[186:189], v[218:221], v[2:5]
	s_barrier
	s_setprio 0
	s_add_i32 s53, s53, 2
	s_add_u32 s51, s51, 0x700000
	s_addc_u32 s52, s52, 0
	s_add_u32 s28, s28, 0x200000
	s_addc_u32 s29, s29, 0
	s_cmp_gt_u32 s53, 61
	s_cbranch_scc0 .LBB0_422
	s_and_b64 vcc, exec, s[16:17]
	s_cbranch_vccz .LBB0_425
	s_barrier

.LBB0_501:
	ds_read_b128 v[146:149], v152
	ds_read_b128 v[156:159], v152 offset:1024
	ds_read_b128 v[160:163], v152 offset:2048
	ds_read_b128 v[164:167], v152 offset:3072
	s_add_u32 s26, s10, 0xfc000
	s_addc_u32 s27, s11, 0
	s_cmpk_eq_i32 s47, 0xdc
	s_cselect_b32 s30, s21, s26
	s_cselect_b32 s31, s5, s27
	s_cselect_b32 s28, s44, s45
	s_cselect_b32 s29, s19, s46
	s_add_u32 s26, s30, 0x100000
	s_addc_u32 s27, s31, 0
	s_add_i32 m0, s1, 0xc000
	ds_read_b128 v[186:189], v154
	ds_read_b128 v[190:193], v154 offset:1024
	ds_read_b128 v[194:197], v154 offset:2048
	ds_read_b128 v[198:201], v154 offset:3072
	ds_read_b128 v[202:205], v154 offset:4096
	ds_read_b128 v[206:209], v154 offset:5120
	ds_read_b128 v[210:213], v154 offset:6144
	ds_read_b128 v[214:217], v154 offset:7168
	global_load_lds_dwordx4 v138, s[10:11]
	s_add_i32 m0, s1, 0xe000
	s_nop 0
	global_load_lds_dwordx4 v140, s[10:11]
	ds_read_b128 v[168:171], v153
	ds_read_b128 v[172:175], v153 offset:1024
	ds_read_b128 v[178:181], v153 offset:2048
	ds_read_b128 v[182:185], v153 offset:3072
	s_waitcnt vmcnt(8)
	s_waitcnt lgkmcnt(4)
	s_setprio 1
	s_barrier
	v_mfma_f32_16x16x32_bf16 v[126:129], v[146:149], v[186:189], v[126:129]
	v_mfma_f32_16x16x32_bf16 v[126:129], v[156:159], v[190:193], v[126:129]
	v_mfma_f32_16x16x32_bf16 v[110:113], v[146:149], v[194:197], v[110:113]
	v_mfma_f32_16x16x32_bf16 v[110:113], v[156:159], v[198:201], v[110:113]
	v_mfma_f32_16x16x32_bf16 v[94:97], v[146:149], v[202:205], v[94:97]
	v_mfma_f32_16x16x32_bf16 v[94:97], v[156:159], v[206:209], v[94:97]
	v_mfma_f32_16x16x32_bf16 v[78:81], v[146:149], v[210:213], v[78:81]
	v_mfma_f32_16x16x32_bf16 v[78:81], v[156:159], v[214:217], v[78:81]
	v_mfma_f32_16x16x32_bf16 v[122:125], v[160:163], v[186:189], v[122:125]
	v_mfma_f32_16x16x32_bf16 v[122:125], v[164:167], v[190:193], v[122:125]
	v_mfma_f32_16x16x32_bf16 v[106:109], v[160:163], v[194:197], v[106:109]
	v_mfma_f32_16x16x32_bf16 v[106:109], v[164:167], v[198:201], v[106:109]
	v_mfma_f32_16x16x32_bf16 v[90:93], v[160:163], v[202:205], v[90:93]
	v_mfma_f32_16x16x32_bf16 v[90:93], v[164:167], v[206:209], v[90:93]
	v_mfma_f32_16x16x32_bf16 v[74:77], v[160:163], v[210:213], v[74:77]
	v_mfma_f32_16x16x32_bf16 v[74:77], v[164:167], v[214:217], v[74:77]
	s_setprio 0
	s_waitcnt lgkmcnt(0)
	s_setprio 1
	v_mfma_f32_16x16x32_bf16 v[118:121], v[168:171], v[186:189], v[118:121]
	v_mfma_f32_16x16x32_bf16 v[118:121], v[172:175], v[190:193], v[118:121]
	v_mfma_f32_16x16x32_bf16 v[102:105], v[168:171], v[194:197], v[102:105]
	v_mfma_f32_16x16x32_bf16 v[102:105], v[172:175], v[198:201], v[102:105]
	v_mfma_f32_16x16x32_bf16 v[86:89], v[168:171], v[202:205], v[86:89]
	v_mfma_f32_16x16x32_bf16 v[86:89], v[172:175], v[206:209], v[86:89]
	v_mfma_f32_16x16x32_bf16 v[70:73], v[168:171], v[210:213], v[70:73]
	v_mfma_f32_16x16x32_bf16 v[70:73], v[172:175], v[214:217], v[70:73]
	v_mfma_f32_16x16x32_bf16 v[114:117], v[178:181], v[186:189], v[114:117]
	v_mfma_f32_16x16x32_bf16 v[114:117], v[182:185], v[190:193], v[114:117]
	v_mfma_f32_16x16x32_bf16 v[98:101], v[178:181], v[194:197], v[98:101]
	v_mfma_f32_16x16x32_bf16 v[98:101], v[182:185], v[198:201], v[98:101]
	v_mfma_f32_16x16x32_bf16 v[82:85], v[178:181], v[202:205], v[82:85]
	v_mfma_f32_16x16x32_bf16 v[82:85], v[182:185], v[206:209], v[82:85]
	v_mfma_f32_16x16x32_bf16 v[66:69], v[178:181], v[210:213], v[66:69]
	v_mfma_f32_16x16x32_bf16 v[66:69], v[182:185], v[214:217], v[66:69]
	s_barrier
	s_setprio 0
	s_add_i32 s48, s41, s0
	s_mov_b32 m0, s48
	ds_read_b128 v[186:189], v154 offset:16384
	ds_read_b128 v[190:193], v154 offset:17408
	ds_read_b128 v[194:197], v154 offset:18432
	ds_read_b128 v[198:201], v154 offset:19456
	ds_read_b128 v[202:205], v154 offset:20480
	ds_read_b128 v[206:209], v154 offset:21504
	ds_read_b128 v[210:213], v154 offset:22528
	ds_read_b128 v[214:217], v154 offset:23552
	global_load_lds_dwordx4 v132, s[28:29]
	s_add_i32 m0, s48, 0x2000
	s_add_u32 s48, s28, 0x4000
	s_addc_u32 s49, s29, 0
	s_add_i32 s50, s42, s0
	global_load_lds_dwordx4 v136, s[28:29]
	s_mov_b32 m0, s50
	s_nop 0
	global_load_lds_dwordx4 v132, s[48:49]
	s_add_i32 m0, s50, 0x2000
	s_nop 0
	global_load_lds_dwordx4 v136, s[48:49]
	s_mov_b32 m0, s1
	s_nop 0
	global_load_lds_dwordx4 v130, s[30:31]
	s_mov_b32 m0, s33
	s_nop 0
	global_load_lds_dwordx4 v134, s[30:31]
	s_waitcnt vmcnt(8)
	s_waitcnt lgkmcnt(0)
	s_setprio 1
	s_barrier
	v_mfma_f32_16x16x32_bf16 v[62:65], v[146:149], v[186:189], v[62:65]
	v_mfma_f32_16x16x32_bf16 v[62:65], v[156:159], v[190:193], v[62:65]
	v_mfma_f32_16x16x32_bf16 v[46:49], v[146:149], v[194:197], v[46:49]
	v_mfma_f32_16x16x32_bf16 v[46:49], v[156:159], v[198:201], v[46:49]
	v_mfma_f32_16x16x32_bf16 v[30:33], v[146:149], v[202:205], v[30:33]
	v_mfma_f32_16x16x32_bf16 v[30:33], v[156:159], v[206:209], v[30:33]
	v_mfma_f32_16x16x32_bf16 v[14:17], v[146:149], v[210:213], v[14:17]
	v_mfma_f32_16x16x32_bf16 v[14:17], v[156:159], v[214:217], v[14:17]
	v_mfma_f32_16x16x32_bf16 v[58:61], v[160:163], v[186:189], v[58:61]
	v_mfma_f32_16x16x32_bf16 v[58:61], v[164:167], v[190:193], v[58:61]
	v_mfma_f32_16x16x32_bf16 v[42:45], v[160:163], v[194:197], v[42:45]
	v_mfma_f32_16x16x32_bf16 v[42:45], v[164:167], v[198:201], v[42:45]
	v_mfma_f32_16x16x32_bf16 v[26:29], v[160:163], v[202:205], v[26:29]
	v_mfma_f32_16x16x32_bf16 v[26:29], v[164:167], v[206:209], v[26:29]
	v_mfma_f32_16x16x32_bf16 v[10:13], v[160:163], v[210:213], v[10:13]
	v_mfma_f32_16x16x32_bf16 v[10:13], v[164:167], v[214:217], v[10:13]
	s_setprio 0
	s_setprio 1
	v_mfma_f32_16x16x32_bf16 v[54:57], v[168:171], v[186:189], v[54:57]
	v_mfma_f32_16x16x32_bf16 v[54:57], v[172:175], v[190:193], v[54:57]
	v_mfma_f32_16x16x32_bf16 v[38:41], v[168:171], v[194:197], v[38:41]
	v_mfma_f32_16x16x32_bf16 v[38:41], v[172:175], v[198:201], v[38:41]
	v_mfma_f32_16x16x32_bf16 v[22:25], v[168:171], v[202:205], v[22:25]
	v_mfma_f32_16x16x32_bf16 v[22:25], v[172:175], v[206:209], v[22:25]
	v_mfma_f32_16x16x32_bf16 v[6:9], v[168:171], v[210:213], v[6:9]
	v_mfma_f32_16x16x32_bf16 v[6:9], v[172:175], v[214:217], v[6:9]
	v_mfma_f32_16x16x32_bf16 v[50:53], v[178:181], v[186:189], v[50:53]
	v_mfma_f32_16x16x32_bf16 v[50:53], v[182:185], v[190:193], v[50:53]
	v_mfma_f32_16x16x32_bf16 v[34:37], v[178:181], v[194:197], v[34:37]
	v_mfma_f32_16x16x32_bf16 v[34:37], v[182:185], v[198:201], v[34:37]
	v_mfma_f32_16x16x32_bf16 v[18:21], v[178:181], v[202:205], v[18:21]
	v_mfma_f32_16x16x32_bf16 v[18:21], v[182:185], v[206:209], v[18:21]
	v_mfma_f32_16x16x32_bf16 v[2:5], v[178:181], v[210:213], v[2:5]
	v_mfma_f32_16x16x32_bf16 v[2:5], v[182:185], v[214:217], v[2:5]
	s_barrier
	s_setprio 0
	s_add_i32 s48, 0, 0x18000
	s_add_i32 s49, 0, 0x1c000
	v_add_u32_e32 v164, s48, v151
	v_add_u32_e32 v176, s49, v151
	ds_read_b128 v[146:149], v164
	ds_read_b128 v[156:159], v164 offset:1024
	ds_read_b128 v[160:163], v164 offset:2048
	ds_read_b128 v[164:167], v164 offset:3072
	s_add_u32 s30, s30, 0x4000
	s_addc_u32 s31, s31, 0
	s_mov_b32 m0, s34
	ds_read_b128 v[186:189], v154 offset:32768
	ds_read_b128 v[190:193], v154 offset:33792
	ds_read_b128 v[194:197], v154 offset:34816
	ds_read_b128 v[198:201], v154 offset:35840
	ds_read_b128 v[202:205], v154 offset:36864
	ds_read_b128 v[206:209], v154 offset:37888
	ds_read_b128 v[210:213], v154 offset:38912
	ds_read_b128 v[214:217], v154 offset:39936
	global_load_lds_dwordx4 v130, s[30:31]
	s_mov_b32 m0, s35
	s_nop 0
	global_load_lds_dwordx4 v134, s[30:31]
	ds_read_b128 v[168:171], v176
	ds_read_b128 v[172:175], v176 offset:1024
	ds_read_b128 v[178:181], v176 offset:2048
	ds_read_b128 v[182:185], v176 offset:3072
	s_waitcnt vmcnt(8)
	s_waitcnt lgkmcnt(4)
	s_setprio 1
	s_barrier
	v_mfma_f32_16x16x32_bf16 v[126:129], v[146:149], v[186:189], v[126:129]
	v_mfma_f32_16x16x32_bf16 v[126:129], v[156:159], v[190:193], v[126:129]
	v_mfma_f32_16x16x32_bf16 v[110:113], v[146:149], v[194:197], v[110:113]
	v_mfma_f32_16x16x32_bf16 v[110:113], v[156:159], v[198:201], v[110:113]
	v_mfma_f32_16x16x32_bf16 v[94:97], v[146:149], v[202:205], v[94:97]
	v_mfma_f32_16x16x32_bf16 v[94:97], v[156:159], v[206:209], v[94:97]
	v_mfma_f32_16x16x32_bf16 v[78:81], v[146:149], v[210:213], v[78:81]
	v_mfma_f32_16x16x32_bf16 v[78:81], v[156:159], v[214:217], v[78:81]
	v_mfma_f32_16x16x32_bf16 v[122:125], v[160:163], v[186:189], v[122:125]
	v_mfma_f32_16x16x32_bf16 v[122:125], v[164:167], v[190:193], v[122:125]
	v_mfma_f32_16x16x32_bf16 v[106:109], v[160:163], v[194:197], v[106:109]
	v_mfma_f32_16x16x32_bf16 v[106:109], v[164:167], v[198:201], v[106:109]
	v_mfma_f32_16x16x32_bf16 v[90:93], v[160:163], v[202:205], v[90:93]
	v_mfma_f32_16x16x32_bf16 v[90:93], v[164:167], v[206:209], v[90:93]
	v_mfma_f32_16x16x32_bf16 v[74:77], v[160:163], v[210:213], v[74:77]
	v_mfma_f32_16x16x32_bf16 v[74:77], v[164:167], v[214:217], v[74:77]
	s_setprio 0
	s_waitcnt lgkmcnt(0)
	s_setprio 1
	v_mfma_f32_16x16x32_bf16 v[118:121], v[168:171], v[186:189], v[118:121]
	v_mfma_f32_16x16x32_bf16 v[118:121], v[172:175], v[190:193], v[118:121]
	v_mfma_f32_16x16x32_bf16 v[102:105], v[168:171], v[194:197], v[102:105]
	v_mfma_f32_16x16x32_bf16 v[102:105], v[172:175], v[198:201], v[102:105]
	v_mfma_f32_16x16x32_bf16 v[86:89], v[168:171], v[202:205], v[86:89]
	v_mfma_f32_16x16x32_bf16 v[86:89], v[172:175], v[206:209], v[86:89]
	v_mfma_f32_16x16x32_bf16 v[70:73], v[168:171], v[210:213], v[70:73]
	v_mfma_f32_16x16x32_bf16 v[70:73], v[172:175], v[214:217], v[70:73]
	v_mfma_f32_16x16x32_bf16 v[114:117], v[178:181], v[186:189], v[114:117]
	v_mfma_f32_16x16x32_bf16 v[114:117], v[182:185], v[190:193], v[114:117]
	v_mfma_f32_16x16x32_bf16 v[98:101], v[178:181], v[194:197], v[98:101]
	v_mfma_f32_16x16x32_bf16 v[98:101], v[182:185], v[198:201], v[98:101]
	v_mfma_f32_16x16x32_bf16 v[82:85], v[178:181], v[202:205], v[82:85]
	v_mfma_f32_16x16x32_bf16 v[82:85], v[182:185], v[206:209], v[82:85]
	v_mfma_f32_16x16x32_bf16 v[66:69], v[178:181], v[210:213], v[66:69]
	v_mfma_f32_16x16x32_bf16 v[66:69], v[182:185], v[214:217], v[66:69]
	s_barrier
	s_setprio 0
	s_add_u32 s30, s28, 0x80000
	s_addc_u32 s31, s29, 0
	s_add_i32 s48, s48, s0
	s_mov_b32 m0, s48
	ds_read_b128 v[186:189], v154 offset:49152
	ds_read_b128 v[190:193], v154 offset:50176
	ds_read_b128 v[194:197], v154 offset:51200
	ds_read_b128 v[198:201], v154 offset:52224
	ds_read_b128 v[202:205], v154 offset:53248
	ds_read_b128 v[206:209], v154 offset:54272
	ds_read_b128 v[210:213], v154 offset:55296
	ds_read_b128 v[214:217], v154 offset:56320
	global_load_lds_dwordx4 v132, s[30:31]
	s_add_i32 m0, s48, 0x2000
	s_add_u32 s28, s28, 0x84000
	s_addc_u32 s29, s29, 0
	global_load_lds_dwordx4 v136, s[30:31]
	s_add_i32 s30, s49, s0
	s_mov_b32 m0, s30
	s_nop 0
	global_load_lds_dwordx4 v132, s[28:29]
	s_add_i32 m0, s30, 0x2000
	s_nop 0
	global_load_lds_dwordx4 v136, s[28:29]
	s_mov_b32 m0, s39
	s_nop 0
	global_load_lds_dwordx4 v130, s[26:27]
	s_mov_b32 m0, s40
	s_nop 0
	global_load_lds_dwordx4 v134, s[26:27]
	s_waitcnt vmcnt(8)
	s_waitcnt lgkmcnt(0)
	s_setprio 1
	s_barrier
	v_mfma_f32_16x16x32_bf16 v[62:65], v[146:149], v[186:189], v[62:65]
	v_mfma_f32_16x16x32_bf16 v[62:65], v[156:159], v[190:193], v[62:65]
	v_mfma_f32_16x16x32_bf16 v[46:49], v[146:149], v[194:197], v[46:49]
	v_mfma_f32_16x16x32_bf16 v[46:49], v[156:159], v[198:201], v[46:49]
	v_mfma_f32_16x16x32_bf16 v[30:33], v[146:149], v[202:205], v[30:33]
	v_mfma_f32_16x16x32_bf16 v[30:33], v[156:159], v[206:209], v[30:33]
	v_mfma_f32_16x16x32_bf16 v[14:17], v[146:149], v[210:213], v[14:17]
	v_mfma_f32_16x16x32_bf16 v[14:17], v[156:159], v[214:217], v[14:17]
	v_mfma_f32_16x16x32_bf16 v[58:61], v[160:163], v[186:189], v[58:61]
	v_mfma_f32_16x16x32_bf16 v[58:61], v[164:167], v[190:193], v[58:61]
	v_mfma_f32_16x16x32_bf16 v[42:45], v[160:163], v[194:197], v[42:45]
	v_mfma_f32_16x16x32_bf16 v[42:45], v[164:167], v[198:201], v[42:45]
	v_mfma_f32_16x16x32_bf16 v[26:29], v[160:163], v[202:205], v[26:29]
	v_mfma_f32_16x16x32_bf16 v[26:29], v[164:167], v[206:209], v[26:29]
	v_mfma_f32_16x16x32_bf16 v[10:13], v[160:163], v[210:213], v[10:13]
	v_mfma_f32_16x16x32_bf16 v[10:13], v[164:167], v[214:217], v[10:13]
	s_setprio 0
	s_setprio 1
	v_mfma_f32_16x16x32_bf16 v[54:57], v[168:171], v[186:189], v[54:57]
	v_mfma_f32_16x16x32_bf16 v[54:57], v[172:175], v[190:193], v[54:57]
	v_mfma_f32_16x16x32_bf16 v[38:41], v[168:171], v[194:197], v[38:41]
	v_mfma_f32_16x16x32_bf16 v[38:41], v[172:175], v[198:201], v[38:41]
	v_mfma_f32_16x16x32_bf16 v[22:25], v[168:171], v[202:205], v[22:25]
	v_mfma_f32_16x16x32_bf16 v[22:25], v[172:175], v[206:209], v[22:25]
	v_mfma_f32_16x16x32_bf16 v[6:9], v[168:171], v[210:213], v[6:9]
	v_mfma_f32_16x16x32_bf16 v[6:9], v[172:175], v[214:217], v[6:9]
	v_mfma_f32_16x16x32_bf16 v[50:53], v[178:181], v[186:189], v[50:53]
	v_mfma_f32_16x16x32_bf16 v[50:53], v[182:185], v[190:193], v[50:53]
	v_mfma_f32_16x16x32_bf16 v[34:37], v[178:181], v[194:197], v[34:37]
	v_mfma_f32_16x16x32_bf16 v[34:37], v[182:185], v[198:201], v[34:37]
	v_mfma_f32_16x16x32_bf16 v[18:21], v[178:181], v[202:205], v[18:21]
	v_mfma_f32_16x16x32_bf16 v[18:21], v[182:185], v[206:209], v[18:21]
	v_mfma_f32_16x16x32_bf16 v[2:5], v[178:181], v[210:213], v[2:5]
	v_mfma_f32_16x16x32_bf16 v[2:5], v[182:185], v[214:217], v[2:5]
	s_barrier
	s_setprio 0
	s_add_i32 s47, s47, 2
	s_add_u32 s45, s45, 0x100000
	s_addc_u32 s46, s46, 0
	s_add_u32 s10, s10, 0x200000
	s_addc_u32 s11, s11, 0
	s_cmpk_gt_u32 s47, 0xdd
	s_cbranch_scc0 .LBB0_501
	s_and_b64 vcc, exec, s[16:17]
	s_cbranch_vccz .LBB0_504
	s_barrier

.LBB0_801:
	ds_read_b128 v[130:133], v179
	ds_read_b128 v[134:137], v179 offset:1024
	ds_read_b128 v[156:159], v179 offset:2048
	ds_read_b128 v[160:163], v179 offset:3072
	s_add_u32 s26, s12, 0xfc000
	s_addc_u32 s27, s13, 0
	s_cmp_eq_u32 s47, 60
	s_cselect_b32 s30, s5, s26
	s_cselect_b32 s31, s3, s27
	s_cselect_b32 s28, s21, s45
	s_cselect_b32 s29, s19, s46
	s_add_u32 s26, s30, 0x100000
	s_addc_u32 s27, s31, 0
	s_add_i32 m0, s1, 0xc000
	ds_read_b128 v[190:193], v181
	ds_read_b128 v[194:197], v181 offset:1024
	ds_read_b128 v[198:201], v181 offset:2048
	ds_read_b128 v[202:205], v181 offset:3072
	ds_read_b128 v[206:209], v181 offset:4096
	ds_read_b128 v[210:213], v181 offset:5120
	ds_read_b128 v[214:217], v181 offset:6144
	ds_read_b128 v[218:221], v181 offset:7168
	global_load_lds_dwordx4 v148, s[12:13]
	s_add_i32 m0, s1, 0xe000
	s_nop 0
	global_load_lds_dwordx4 v150, s[12:13]
	ds_read_b128 v[164:167], v180
	ds_read_b128 v[168:171], v180 offset:1024
	ds_read_b128 v[172:175], v180 offset:2048
	ds_read_b128 v[186:189], v180 offset:3072
	s_waitcnt vmcnt(8)
	s_waitcnt lgkmcnt(4)
	s_setprio 1
	s_barrier
	v_mfma_f32_16x16x32_bf16 v[126:129], v[130:133], v[190:193], v[126:129]
	v_mfma_f32_16x16x32_bf16 v[126:129], v[134:137], v[194:197], v[126:129]
	v_mfma_f32_16x16x32_bf16 v[110:113], v[130:133], v[198:201], v[110:113]
	v_mfma_f32_16x16x32_bf16 v[110:113], v[134:137], v[202:205], v[110:113]
	v_mfma_f32_16x16x32_bf16 v[94:97], v[130:133], v[206:209], v[94:97]
	v_mfma_f32_16x16x32_bf16 v[94:97], v[134:137], v[210:213], v[94:97]
	v_mfma_f32_16x16x32_bf16 v[78:81], v[130:133], v[214:217], v[78:81]
	v_mfma_f32_16x16x32_bf16 v[78:81], v[134:137], v[218:221], v[78:81]
	v_mfma_f32_16x16x32_bf16 v[122:125], v[156:159], v[190:193], v[122:125]
	v_mfma_f32_16x16x32_bf16 v[122:125], v[160:163], v[194:197], v[122:125]
	v_mfma_f32_16x16x32_bf16 v[106:109], v[156:159], v[198:201], v[106:109]
	v_mfma_f32_16x16x32_bf16 v[106:109], v[160:163], v[202:205], v[106:109]
	v_mfma_f32_16x16x32_bf16 v[90:93], v[156:159], v[206:209], v[90:93]
	v_mfma_f32_16x16x32_bf16 v[90:93], v[160:163], v[210:213], v[90:93]
	v_mfma_f32_16x16x32_bf16 v[74:77], v[156:159], v[214:217], v[74:77]
	v_mfma_f32_16x16x32_bf16 v[74:77], v[160:163], v[218:221], v[74:77]
	s_setprio 0
	s_waitcnt lgkmcnt(0)
	s_setprio 1
	v_mfma_f32_16x16x32_bf16 v[118:121], v[164:167], v[190:193], v[118:121]
	v_mfma_f32_16x16x32_bf16 v[118:121], v[168:171], v[194:197], v[118:121]
	v_mfma_f32_16x16x32_bf16 v[102:105], v[164:167], v[198:201], v[102:105]
	v_mfma_f32_16x16x32_bf16 v[102:105], v[168:171], v[202:205], v[102:105]
	v_mfma_f32_16x16x32_bf16 v[86:89], v[164:167], v[206:209], v[86:89]
	v_mfma_f32_16x16x32_bf16 v[86:89], v[168:171], v[210:213], v[86:89]
	v_mfma_f32_16x16x32_bf16 v[70:73], v[164:167], v[214:217], v[70:73]
	v_mfma_f32_16x16x32_bf16 v[70:73], v[168:171], v[218:221], v[70:73]
	v_mfma_f32_16x16x32_bf16 v[114:117], v[172:175], v[190:193], v[114:117]
	v_mfma_f32_16x16x32_bf16 v[114:117], v[186:189], v[194:197], v[114:117]
	v_mfma_f32_16x16x32_bf16 v[98:101], v[172:175], v[198:201], v[98:101]
	v_mfma_f32_16x16x32_bf16 v[98:101], v[186:189], v[202:205], v[98:101]
	v_mfma_f32_16x16x32_bf16 v[82:85], v[172:175], v[206:209], v[82:85]
	v_mfma_f32_16x16x32_bf16 v[82:85], v[186:189], v[210:213], v[82:85]
	v_mfma_f32_16x16x32_bf16 v[66:69], v[172:175], v[214:217], v[66:69]
	v_mfma_f32_16x16x32_bf16 v[66:69], v[186:189], v[218:221], v[66:69]
	s_barrier
	s_setprio 0
	s_add_i32 s48, s42, s0
	s_mov_b32 m0, s48
	ds_read_b128 v[190:193], v181 offset:16384
	ds_read_b128 v[194:197], v181 offset:17408
	ds_read_b128 v[198:201], v181 offset:18432
	ds_read_b128 v[202:205], v181 offset:19456
	ds_read_b128 v[206:209], v181 offset:20480
	ds_read_b128 v[210:213], v181 offset:21504
	ds_read_b128 v[214:217], v181 offset:22528
	ds_read_b128 v[218:221], v181 offset:23552
	global_load_lds_dwordx4 v140, s[28:29]
	s_add_i32 m0, s48, 0x2000
	s_add_u32 s48, s28, 0x4000
	s_addc_u32 s49, s29, 0
	s_add_i32 s50, s43, s0
	global_load_lds_dwordx4 v144, s[28:29]
	s_mov_b32 m0, s50
	s_nop 0
	global_load_lds_dwordx4 v140, s[48:49]
	s_add_i32 m0, s50, 0x2000
	s_nop 0
	global_load_lds_dwordx4 v144, s[48:49]
	s_mov_b32 m0, s1
	s_nop 0
	global_load_lds_dwordx4 v138, s[30:31]
	s_mov_b32 m0, s33
	s_nop 0
	global_load_lds_dwordx4 v142, s[30:31]
	s_waitcnt vmcnt(8)
	s_waitcnt lgkmcnt(0)
	s_setprio 1
	s_barrier
	v_mfma_f32_16x16x32_bf16 v[62:65], v[130:133], v[190:193], v[62:65]
	v_mfma_f32_16x16x32_bf16 v[62:65], v[134:137], v[194:197], v[62:65]
	v_mfma_f32_16x16x32_bf16 v[46:49], v[130:133], v[198:201], v[46:49]
	v_mfma_f32_16x16x32_bf16 v[46:49], v[134:137], v[202:205], v[46:49]
	v_mfma_f32_16x16x32_bf16 v[30:33], v[130:133], v[206:209], v[30:33]
	v_mfma_f32_16x16x32_bf16 v[30:33], v[134:137], v[210:213], v[30:33]
	v_mfma_f32_16x16x32_bf16 v[14:17], v[130:133], v[214:217], v[14:17]
	v_mfma_f32_16x16x32_bf16 v[14:17], v[134:137], v[218:221], v[14:17]
	v_mfma_f32_16x16x32_bf16 v[58:61], v[156:159], v[190:193], v[58:61]
	v_mfma_f32_16x16x32_bf16 v[58:61], v[160:163], v[194:197], v[58:61]
	v_mfma_f32_16x16x32_bf16 v[42:45], v[156:159], v[198:201], v[42:45]
	v_mfma_f32_16x16x32_bf16 v[42:45], v[160:163], v[202:205], v[42:45]
	v_mfma_f32_16x16x32_bf16 v[26:29], v[156:159], v[206:209], v[26:29]
	v_mfma_f32_16x16x32_bf16 v[26:29], v[160:163], v[210:213], v[26:29]
	v_mfma_f32_16x16x32_bf16 v[10:13], v[156:159], v[214:217], v[10:13]
	v_mfma_f32_16x16x32_bf16 v[10:13], v[160:163], v[218:221], v[10:13]
	s_setprio 0
	s_setprio 1
	v_mfma_f32_16x16x32_bf16 v[54:57], v[164:167], v[190:193], v[54:57]
	v_mfma_f32_16x16x32_bf16 v[54:57], v[168:171], v[194:197], v[54:57]
	v_mfma_f32_16x16x32_bf16 v[38:41], v[164:167], v[198:201], v[38:41]
	v_mfma_f32_16x16x32_bf16 v[38:41], v[168:171], v[202:205], v[38:41]
	v_mfma_f32_16x16x32_bf16 v[22:25], v[164:167], v[206:209], v[22:25]
	v_mfma_f32_16x16x32_bf16 v[22:25], v[168:171], v[210:213], v[22:25]
	v_mfma_f32_16x16x32_bf16 v[6:9], v[164:167], v[214:217], v[6:9]
	v_mfma_f32_16x16x32_bf16 v[6:9], v[168:171], v[218:221], v[6:9]
	v_mfma_f32_16x16x32_bf16 v[50:53], v[172:175], v[190:193], v[50:53]
	v_mfma_f32_16x16x32_bf16 v[50:53], v[186:189], v[194:197], v[50:53]
	v_mfma_f32_16x16x32_bf16 v[34:37], v[172:175], v[198:201], v[34:37]
	v_mfma_f32_16x16x32_bf16 v[34:37], v[186:189], v[202:205], v[34:37]
	v_mfma_f32_16x16x32_bf16 v[18:21], v[172:175], v[206:209], v[18:21]
	v_mfma_f32_16x16x32_bf16 v[18:21], v[186:189], v[210:213], v[18:21]
	v_mfma_f32_16x16x32_bf16 v[2:5], v[172:175], v[214:217], v[2:5]
	v_mfma_f32_16x16x32_bf16 v[2:5], v[186:189], v[218:221], v[2:5]
	s_barrier
	s_setprio 0
	s_add_i32 s48, 0, 0x18000
	v_add_u32_e32 v146, s48, v178
	s_add_i32 s49, 0, 0x1c000
	ds_read_b128 v[130:133], v146
	ds_read_b128 v[134:137], v146 offset:1024
	ds_read_b128 v[156:159], v146 offset:2048
	ds_read_b128 v[160:163], v146 offset:3072
	v_add_u32_e32 v146, s49, v178
	s_add_u32 s30, s30, 0x4000
	s_addc_u32 s31, s31, 0
	s_mov_b32 m0, s34
	ds_read_b128 v[190:193], v181 offset:32768
	ds_read_b128 v[194:197], v181 offset:33792
	ds_read_b128 v[198:201], v181 offset:34816
	ds_read_b128 v[202:205], v181 offset:35840
	ds_read_b128 v[206:209], v181 offset:36864
	ds_read_b128 v[210:213], v181 offset:37888
	ds_read_b128 v[214:217], v181 offset:38912
	ds_read_b128 v[218:221], v181 offset:39936
	global_load_lds_dwordx4 v138, s[30:31]
	s_mov_b32 m0, s35
	s_nop 0
	global_load_lds_dwordx4 v142, s[30:31]
	ds_read_b128 v[164:167], v146
	ds_read_b128 v[168:171], v146 offset:1024
	ds_read_b128 v[172:175], v146 offset:2048
	ds_read_b128 v[186:189], v146 offset:3072
	s_waitcnt vmcnt(8)
	s_waitcnt lgkmcnt(4)
	s_setprio 1
	s_barrier
	v_mfma_f32_16x16x32_bf16 v[126:129], v[130:133], v[190:193], v[126:129]
	v_mfma_f32_16x16x32_bf16 v[126:129], v[134:137], v[194:197], v[126:129]
	v_mfma_f32_16x16x32_bf16 v[110:113], v[130:133], v[198:201], v[110:113]
	v_mfma_f32_16x16x32_bf16 v[110:113], v[134:137], v[202:205], v[110:113]
	v_mfma_f32_16x16x32_bf16 v[94:97], v[130:133], v[206:209], v[94:97]
	v_mfma_f32_16x16x32_bf16 v[94:97], v[134:137], v[210:213], v[94:97]
	v_mfma_f32_16x16x32_bf16 v[78:81], v[130:133], v[214:217], v[78:81]
	v_mfma_f32_16x16x32_bf16 v[78:81], v[134:137], v[218:221], v[78:81]
	v_mfma_f32_16x16x32_bf16 v[122:125], v[156:159], v[190:193], v[122:125]
	v_mfma_f32_16x16x32_bf16 v[122:125], v[160:163], v[194:197], v[122:125]
	v_mfma_f32_16x16x32_bf16 v[106:109], v[156:159], v[198:201], v[106:109]
	v_mfma_f32_16x16x32_bf16 v[106:109], v[160:163], v[202:205], v[106:109]
	v_mfma_f32_16x16x32_bf16 v[90:93], v[156:159], v[206:209], v[90:93]
	v_mfma_f32_16x16x32_bf16 v[90:93], v[160:163], v[210:213], v[90:93]
	v_mfma_f32_16x16x32_bf16 v[74:77], v[156:159], v[214:217], v[74:77]
	v_mfma_f32_16x16x32_bf16 v[74:77], v[160:163], v[218:221], v[74:77]
	s_setprio 0
	s_waitcnt lgkmcnt(0)
	s_setprio 1
	v_mfma_f32_16x16x32_bf16 v[118:121], v[164:167], v[190:193], v[118:121]
	v_mfma_f32_16x16x32_bf16 v[118:121], v[168:171], v[194:197], v[118:121]
	v_mfma_f32_16x16x32_bf16 v[102:105], v[164:167], v[198:201], v[102:105]
	v_mfma_f32_16x16x32_bf16 v[102:105], v[168:171], v[202:205], v[102:105]
	v_mfma_f32_16x16x32_bf16 v[86:89], v[164:167], v[206:209], v[86:89]
	v_mfma_f32_16x16x32_bf16 v[86:89], v[168:171], v[210:213], v[86:89]
	v_mfma_f32_16x16x32_bf16 v[70:73], v[164:167], v[214:217], v[70:73]
	v_mfma_f32_16x16x32_bf16 v[70:73], v[168:171], v[218:221], v[70:73]
	v_mfma_f32_16x16x32_bf16 v[114:117], v[172:175], v[190:193], v[114:117]
	v_mfma_f32_16x16x32_bf16 v[114:117], v[186:189], v[194:197], v[114:117]
	v_mfma_f32_16x16x32_bf16 v[98:101], v[172:175], v[198:201], v[98:101]
	v_mfma_f32_16x16x32_bf16 v[98:101], v[186:189], v[202:205], v[98:101]
	v_mfma_f32_16x16x32_bf16 v[82:85], v[172:175], v[206:209], v[82:85]
	v_mfma_f32_16x16x32_bf16 v[82:85], v[186:189], v[210:213], v[82:85]
	v_mfma_f32_16x16x32_bf16 v[66:69], v[172:175], v[214:217], v[66:69]
	v_mfma_f32_16x16x32_bf16 v[66:69], v[186:189], v[218:221], v[66:69]
	s_barrier
	s_setprio 0
	s_add_u32 s30, s28, 0x180000
	s_addc_u32 s31, s29, 0
	s_add_i32 s48, s48, s0
	s_mov_b32 m0, s48
	ds_read_b128 v[190:193], v181 offset:49152
	ds_read_b128 v[194:197], v181 offset:50176
	ds_read_b128 v[198:201], v181 offset:51200
	ds_read_b128 v[202:205], v181 offset:52224
	ds_read_b128 v[206:209], v181 offset:53248
	ds_read_b128 v[210:213], v181 offset:54272
	ds_read_b128 v[214:217], v181 offset:55296
	ds_read_b128 v[218:221], v181 offset:56320
	global_load_lds_dwordx4 v140, s[30:31]
	s_add_i32 m0, s48, 0x2000
	s_add_u32 s28, s28, 0x184000
	s_addc_u32 s29, s29, 0
	global_load_lds_dwordx4 v144, s[30:31]
	s_add_i32 s30, s49, s0
	s_mov_b32 m0, s30
	s_nop 0
	global_load_lds_dwordx4 v140, s[28:29]
	s_add_i32 m0, s30, 0x2000
	s_nop 0
	global_load_lds_dwordx4 v144, s[28:29]
	s_mov_b32 m0, s38
	s_nop 0
	global_load_lds_dwordx4 v138, s[26:27]
	s_mov_b32 m0, s39
	s_nop 0
	global_load_lds_dwordx4 v142, s[26:27]
	s_waitcnt vmcnt(8)
	s_waitcnt lgkmcnt(0)
	s_setprio 1
	s_barrier
	v_mfma_f32_16x16x32_bf16 v[62:65], v[130:133], v[190:193], v[62:65]
	v_mfma_f32_16x16x32_bf16 v[62:65], v[134:137], v[194:197], v[62:65]
	v_mfma_f32_16x16x32_bf16 v[46:49], v[130:133], v[198:201], v[46:49]
	v_mfma_f32_16x16x32_bf16 v[46:49], v[134:137], v[202:205], v[46:49]
	v_mfma_f32_16x16x32_bf16 v[30:33], v[130:133], v[206:209], v[30:33]
	v_mfma_f32_16x16x32_bf16 v[30:33], v[134:137], v[210:213], v[30:33]
	v_mfma_f32_16x16x32_bf16 v[14:17], v[130:133], v[214:217], v[14:17]
	v_mfma_f32_16x16x32_bf16 v[14:17], v[134:137], v[218:221], v[14:17]
	v_mfma_f32_16x16x32_bf16 v[58:61], v[156:159], v[190:193], v[58:61]
	v_mfma_f32_16x16x32_bf16 v[58:61], v[160:163], v[194:197], v[58:61]
	v_mfma_f32_16x16x32_bf16 v[42:45], v[156:159], v[198:201], v[42:45]
	v_mfma_f32_16x16x32_bf16 v[42:45], v[160:163], v[202:205], v[42:45]
	v_mfma_f32_16x16x32_bf16 v[26:29], v[156:159], v[206:209], v[26:29]
	v_mfma_f32_16x16x32_bf16 v[26:29], v[160:163], v[210:213], v[26:29]
	v_mfma_f32_16x16x32_bf16 v[10:13], v[156:159], v[214:217], v[10:13]
	v_mfma_f32_16x16x32_bf16 v[10:13], v[160:163], v[218:221], v[10:13]
	s_setprio 0
	s_setprio 1
	v_mfma_f32_16x16x32_bf16 v[54:57], v[164:167], v[190:193], v[54:57]
	v_mfma_f32_16x16x32_bf16 v[54:57], v[168:171], v[194:197], v[54:57]
	v_mfma_f32_16x16x32_bf16 v[38:41], v[164:167], v[198:201], v[38:41]
	v_mfma_f32_16x16x32_bf16 v[38:41], v[168:171], v[202:205], v[38:41]
	v_mfma_f32_16x16x32_bf16 v[22:25], v[164:167], v[206:209], v[22:25]
	v_mfma_f32_16x16x32_bf16 v[22:25], v[168:171], v[210:213], v[22:25]
	v_mfma_f32_16x16x32_bf16 v[6:9], v[164:167], v[214:217], v[6:9]
	v_mfma_f32_16x16x32_bf16 v[6:9], v[168:171], v[218:221], v[6:9]
	v_mfma_f32_16x16x32_bf16 v[50:53], v[172:175], v[190:193], v[50:53]
	v_mfma_f32_16x16x32_bf16 v[50:53], v[186:189], v[194:197], v[50:53]
	v_mfma_f32_16x16x32_bf16 v[34:37], v[172:175], v[198:201], v[34:37]
	v_mfma_f32_16x16x32_bf16 v[34:37], v[186:189], v[202:205], v[34:37]
	v_mfma_f32_16x16x32_bf16 v[18:21], v[172:175], v[206:209], v[18:21]
	v_mfma_f32_16x16x32_bf16 v[18:21], v[186:189], v[210:213], v[18:21]
	v_mfma_f32_16x16x32_bf16 v[2:5], v[172:175], v[214:217], v[2:5]
	v_mfma_f32_16x16x32_bf16 v[2:5], v[186:189], v[218:221], v[2:5]
	s_barrier
	s_setprio 0
	s_add_i32 s47, s47, 2
	s_add_u32 s45, s45, 0x300000
	s_addc_u32 s46, s46, 0
	s_add_u32 s12, s12, 0x200000
	s_addc_u32 s13, s13, 0
	s_cmp_gt_u32 s47, 61
	s_cbranch_scc0 .LBB0_801
	s_and_b64 vcc, exec, s[8:9]
	s_cbranch_vccz .LBB0_804
	s_barrier

.LBB0_1217:
	ds_read_b128 v[146:149], v152
	ds_read_b128 v[156:159], v152 offset:1024
	ds_read_b128 v[160:163], v152 offset:2048
	ds_read_b128 v[164:167], v152 offset:3072
	s_add_u32 s22, s20, 0xfc000
	s_addc_u32 s23, s21, 0
	s_cmp_eq_u32 s43, 60
	s_cselect_b32 s26, s15, s22
	s_cselect_b32 s27, s5, s23
	s_cselect_b32 s24, s40, s41
	s_cselect_b32 s25, s13, s42
	s_add_u32 s22, s26, 0x100000
	s_addc_u32 s23, s27, 0
	s_add_i32 m0, s1, 0xc000
	ds_read_b128 v[184:187], v154
	ds_read_b128 v[188:191], v154 offset:1024
	ds_read_b128 v[192:195], v154 offset:2048
	ds_read_b128 v[196:199], v154 offset:3072
	ds_read_b128 v[206:209], v154 offset:4096
	ds_read_b128 v[212:215], v154 offset:5120
	ds_read_b128 v[220:223], v154 offset:6144
	ds_read_b128 v[224:227], v154 offset:7168
	global_load_lds_dwordx4 v138, s[20:21]
	s_add_i32 m0, s1, 0xe000
	s_nop 0
	global_load_lds_dwordx4 v140, s[20:21]
	ds_read_b128 v[168:171], v153
	ds_read_b128 v[172:175], v153 offset:1024
	ds_read_b128 v[176:179], v153 offset:2048
	ds_read_b128 v[180:183], v153 offset:3072
	s_waitcnt vmcnt(8)
	s_waitcnt lgkmcnt(4)
	s_setprio 1
	s_barrier
	v_mfma_f32_16x16x32_bf16 v[126:129], v[146:149], v[184:187], v[126:129]
	v_mfma_f32_16x16x32_bf16 v[126:129], v[156:159], v[188:191], v[126:129]
	v_mfma_f32_16x16x32_bf16 v[110:113], v[146:149], v[192:195], v[110:113]
	v_mfma_f32_16x16x32_bf16 v[110:113], v[156:159], v[196:199], v[110:113]
	v_mfma_f32_16x16x32_bf16 v[94:97], v[146:149], v[206:209], v[94:97]
	v_mfma_f32_16x16x32_bf16 v[94:97], v[156:159], v[212:215], v[94:97]
	v_mfma_f32_16x16x32_bf16 v[78:81], v[146:149], v[220:223], v[78:81]
	v_mfma_f32_16x16x32_bf16 v[78:81], v[156:159], v[224:227], v[78:81]
	v_mfma_f32_16x16x32_bf16 v[122:125], v[160:163], v[184:187], v[122:125]
	v_mfma_f32_16x16x32_bf16 v[122:125], v[164:167], v[188:191], v[122:125]
	v_mfma_f32_16x16x32_bf16 v[106:109], v[160:163], v[192:195], v[106:109]
	v_mfma_f32_16x16x32_bf16 v[106:109], v[164:167], v[196:199], v[106:109]
	v_mfma_f32_16x16x32_bf16 v[90:93], v[160:163], v[206:209], v[90:93]
	v_mfma_f32_16x16x32_bf16 v[90:93], v[164:167], v[212:215], v[90:93]
	v_mfma_f32_16x16x32_bf16 v[74:77], v[160:163], v[220:223], v[74:77]
	v_mfma_f32_16x16x32_bf16 v[74:77], v[164:167], v[224:227], v[74:77]
	s_setprio 0
	s_waitcnt lgkmcnt(0)
	s_setprio 1
	v_mfma_f32_16x16x32_bf16 v[118:121], v[168:171], v[184:187], v[118:121]
	v_mfma_f32_16x16x32_bf16 v[118:121], v[172:175], v[188:191], v[118:121]
	v_mfma_f32_16x16x32_bf16 v[102:105], v[168:171], v[192:195], v[102:105]
	v_mfma_f32_16x16x32_bf16 v[102:105], v[172:175], v[196:199], v[102:105]
	v_mfma_f32_16x16x32_bf16 v[86:89], v[168:171], v[206:209], v[86:89]
	v_mfma_f32_16x16x32_bf16 v[86:89], v[172:175], v[212:215], v[86:89]
	v_mfma_f32_16x16x32_bf16 v[70:73], v[168:171], v[220:223], v[70:73]
	v_mfma_f32_16x16x32_bf16 v[70:73], v[172:175], v[224:227], v[70:73]
	v_mfma_f32_16x16x32_bf16 v[114:117], v[176:179], v[184:187], v[114:117]
	v_mfma_f32_16x16x32_bf16 v[114:117], v[180:183], v[188:191], v[114:117]
	v_mfma_f32_16x16x32_bf16 v[98:101], v[176:179], v[192:195], v[98:101]
	v_mfma_f32_16x16x32_bf16 v[98:101], v[180:183], v[196:199], v[98:101]
	v_mfma_f32_16x16x32_bf16 v[82:85], v[176:179], v[206:209], v[82:85]
	v_mfma_f32_16x16x32_bf16 v[82:85], v[180:183], v[212:215], v[82:85]
	v_mfma_f32_16x16x32_bf16 v[66:69], v[176:179], v[220:223], v[66:69]
	v_mfma_f32_16x16x32_bf16 v[66:69], v[180:183], v[224:227], v[66:69]
	s_barrier
	s_setprio 0
	s_add_i32 s44, s37, s0
	s_mov_b32 m0, s44
	ds_read_b128 v[184:187], v154 offset:16384
	ds_read_b128 v[188:191], v154 offset:17408
	ds_read_b128 v[192:195], v154 offset:18432
	ds_read_b128 v[196:199], v154 offset:19456
	ds_read_b128 v[206:209], v154 offset:20480
	ds_read_b128 v[212:215], v154 offset:21504
	ds_read_b128 v[220:223], v154 offset:22528
	ds_read_b128 v[224:227], v154 offset:23552
	global_load_lds_dwordx4 v132, s[24:25]
	s_add_i32 m0, s44, 0x2000
	s_add_u32 s44, s24, 0x4000
	s_addc_u32 s45, s25, 0
	s_add_i32 s46, s38, s0
	global_load_lds_dwordx4 v136, s[24:25]
	s_mov_b32 m0, s46
	s_nop 0
	global_load_lds_dwordx4 v132, s[44:45]
	s_add_i32 m0, s46, 0x2000
	s_nop 0
	global_load_lds_dwordx4 v136, s[44:45]
	s_mov_b32 m0, s1
	s_nop 0
	global_load_lds_dwordx4 v130, s[26:27]
	s_mov_b32 m0, s28
	s_nop 0
	global_load_lds_dwordx4 v134, s[26:27]
	s_waitcnt vmcnt(8)
	s_waitcnt lgkmcnt(0)
	s_setprio 1
	s_barrier
	v_mfma_f32_16x16x32_bf16 v[62:65], v[146:149], v[184:187], v[62:65]
	v_mfma_f32_16x16x32_bf16 v[62:65], v[156:159], v[188:191], v[62:65]
	v_mfma_f32_16x16x32_bf16 v[46:49], v[146:149], v[192:195], v[46:49]
	v_mfma_f32_16x16x32_bf16 v[46:49], v[156:159], v[196:199], v[46:49]
	v_mfma_f32_16x16x32_bf16 v[30:33], v[146:149], v[206:209], v[30:33]
	v_mfma_f32_16x16x32_bf16 v[30:33], v[156:159], v[212:215], v[30:33]
	v_mfma_f32_16x16x32_bf16 v[14:17], v[146:149], v[220:223], v[14:17]
	v_mfma_f32_16x16x32_bf16 v[14:17], v[156:159], v[224:227], v[14:17]
	v_mfma_f32_16x16x32_bf16 v[58:61], v[160:163], v[184:187], v[58:61]
	v_mfma_f32_16x16x32_bf16 v[58:61], v[164:167], v[188:191], v[58:61]
	v_mfma_f32_16x16x32_bf16 v[42:45], v[160:163], v[192:195], v[42:45]
	v_mfma_f32_16x16x32_bf16 v[42:45], v[164:167], v[196:199], v[42:45]
	v_mfma_f32_16x16x32_bf16 v[26:29], v[160:163], v[206:209], v[26:29]
	v_mfma_f32_16x16x32_bf16 v[26:29], v[164:167], v[212:215], v[26:29]
	v_mfma_f32_16x16x32_bf16 v[10:13], v[160:163], v[220:223], v[10:13]
	v_mfma_f32_16x16x32_bf16 v[10:13], v[164:167], v[224:227], v[10:13]
	s_setprio 0
	s_setprio 1
	v_mfma_f32_16x16x32_bf16 v[54:57], v[168:171], v[184:187], v[54:57]
	v_mfma_f32_16x16x32_bf16 v[54:57], v[172:175], v[188:191], v[54:57]
	v_mfma_f32_16x16x32_bf16 v[38:41], v[168:171], v[192:195], v[38:41]
	v_mfma_f32_16x16x32_bf16 v[38:41], v[172:175], v[196:199], v[38:41]
	v_mfma_f32_16x16x32_bf16 v[22:25], v[168:171], v[206:209], v[22:25]
	v_mfma_f32_16x16x32_bf16 v[22:25], v[172:175], v[212:215], v[22:25]
	v_mfma_f32_16x16x32_bf16 v[6:9], v[168:171], v[220:223], v[6:9]
	v_mfma_f32_16x16x32_bf16 v[6:9], v[172:175], v[224:227], v[6:9]
	v_mfma_f32_16x16x32_bf16 v[50:53], v[176:179], v[184:187], v[50:53]
	v_mfma_f32_16x16x32_bf16 v[50:53], v[180:183], v[188:191], v[50:53]
	v_mfma_f32_16x16x32_bf16 v[34:37], v[176:179], v[192:195], v[34:37]
	v_mfma_f32_16x16x32_bf16 v[34:37], v[180:183], v[196:199], v[34:37]
	v_mfma_f32_16x16x32_bf16 v[18:21], v[176:179], v[206:209], v[18:21]
	v_mfma_f32_16x16x32_bf16 v[18:21], v[180:183], v[212:215], v[18:21]
	v_mfma_f32_16x16x32_bf16 v[2:5], v[176:179], v[220:223], v[2:5]
	v_mfma_f32_16x16x32_bf16 v[2:5], v[180:183], v[224:227], v[2:5]
	s_barrier
	s_setprio 0
	s_add_i32 s44, 0, 0x18000
	v_add_u32_e32 v155, s44, v151
	s_add_i32 s45, 0, 0x1c000
	ds_read_b128 v[146:149], v155
	ds_read_b128 v[156:159], v155 offset:1024
	ds_read_b128 v[160:163], v155 offset:2048
	ds_read_b128 v[164:167], v155 offset:3072
	v_add_u32_e32 v155, s45, v151
	s_add_u32 s26, s26, 0x4000
	s_addc_u32 s27, s27, 0
	s_mov_b32 m0, s29
	ds_read_b128 v[184:187], v154 offset:32768
	ds_read_b128 v[188:191], v154 offset:33792
	ds_read_b128 v[192:195], v154 offset:34816
	ds_read_b128 v[196:199], v154 offset:35840
	ds_read_b128 v[206:209], v154 offset:36864
	ds_read_b128 v[212:215], v154 offset:37888
	ds_read_b128 v[220:223], v154 offset:38912
	ds_read_b128 v[224:227], v154 offset:39936
	global_load_lds_dwordx4 v130, s[26:27]
	s_mov_b32 m0, s30
	s_nop 0
	global_load_lds_dwordx4 v134, s[26:27]
	ds_read_b128 v[168:171], v155
	ds_read_b128 v[172:175], v155 offset:1024
	ds_read_b128 v[176:179], v155 offset:2048
	ds_read_b128 v[180:183], v155 offset:3072
	s_waitcnt vmcnt(8)
	s_waitcnt lgkmcnt(4)
	s_setprio 1
	s_barrier
	v_mfma_f32_16x16x32_bf16 v[126:129], v[146:149], v[184:187], v[126:129]
	v_mfma_f32_16x16x32_bf16 v[126:129], v[156:159], v[188:191], v[126:129]
	v_mfma_f32_16x16x32_bf16 v[110:113], v[146:149], v[192:195], v[110:113]
	v_mfma_f32_16x16x32_bf16 v[110:113], v[156:159], v[196:199], v[110:113]
	v_mfma_f32_16x16x32_bf16 v[94:97], v[146:149], v[206:209], v[94:97]
	v_mfma_f32_16x16x32_bf16 v[94:97], v[156:159], v[212:215], v[94:97]
	v_mfma_f32_16x16x32_bf16 v[78:81], v[146:149], v[220:223], v[78:81]
	v_mfma_f32_16x16x32_bf16 v[78:81], v[156:159], v[224:227], v[78:81]
	v_mfma_f32_16x16x32_bf16 v[122:125], v[160:163], v[184:187], v[122:125]
	v_mfma_f32_16x16x32_bf16 v[122:125], v[164:167], v[188:191], v[122:125]
	v_mfma_f32_16x16x32_bf16 v[106:109], v[160:163], v[192:195], v[106:109]
	v_mfma_f32_16x16x32_bf16 v[106:109], v[164:167], v[196:199], v[106:109]
	v_mfma_f32_16x16x32_bf16 v[90:93], v[160:163], v[206:209], v[90:93]
	v_mfma_f32_16x16x32_bf16 v[90:93], v[164:167], v[212:215], v[90:93]
	v_mfma_f32_16x16x32_bf16 v[74:77], v[160:163], v[220:223], v[74:77]
	v_mfma_f32_16x16x32_bf16 v[74:77], v[164:167], v[224:227], v[74:77]
	s_setprio 0
	s_waitcnt lgkmcnt(0)
	s_setprio 1
	v_mfma_f32_16x16x32_bf16 v[118:121], v[168:171], v[184:187], v[118:121]
	v_mfma_f32_16x16x32_bf16 v[118:121], v[172:175], v[188:191], v[118:121]
	v_mfma_f32_16x16x32_bf16 v[102:105], v[168:171], v[192:195], v[102:105]
	v_mfma_f32_16x16x32_bf16 v[102:105], v[172:175], v[196:199], v[102:105]
	v_mfma_f32_16x16x32_bf16 v[86:89], v[168:171], v[206:209], v[86:89]
	v_mfma_f32_16x16x32_bf16 v[86:89], v[172:175], v[212:215], v[86:89]
	v_mfma_f32_16x16x32_bf16 v[70:73], v[168:171], v[220:223], v[70:73]
	v_mfma_f32_16x16x32_bf16 v[70:73], v[172:175], v[224:227], v[70:73]
	v_mfma_f32_16x16x32_bf16 v[114:117], v[176:179], v[184:187], v[114:117]
	v_mfma_f32_16x16x32_bf16 v[114:117], v[180:183], v[188:191], v[114:117]
	v_mfma_f32_16x16x32_bf16 v[98:101], v[176:179], v[192:195], v[98:101]
	v_mfma_f32_16x16x32_bf16 v[98:101], v[180:183], v[196:199], v[98:101]
	v_mfma_f32_16x16x32_bf16 v[82:85], v[176:179], v[206:209], v[82:85]
	v_mfma_f32_16x16x32_bf16 v[82:85], v[180:183], v[212:215], v[82:85]
	v_mfma_f32_16x16x32_bf16 v[66:69], v[176:179], v[220:223], v[66:69]
	v_mfma_f32_16x16x32_bf16 v[66:69], v[180:183], v[224:227], v[66:69]
	s_barrier
	s_setprio 0
	s_add_u32 s26, s24, 0x80000
	s_addc_u32 s27, s25, 0
	s_add_i32 s44, s44, s0
	s_mov_b32 m0, s44
	ds_read_b128 v[184:187], v154 offset:49152
	ds_read_b128 v[188:191], v154 offset:50176
	ds_read_b128 v[192:195], v154 offset:51200
	ds_read_b128 v[196:199], v154 offset:52224
	ds_read_b128 v[206:209], v154 offset:53248
	ds_read_b128 v[212:215], v154 offset:54272
	ds_read_b128 v[220:223], v154 offset:55296
	ds_read_b128 v[224:227], v154 offset:56320
	global_load_lds_dwordx4 v132, s[26:27]
	s_add_i32 m0, s44, 0x2000
	s_add_u32 s24, s24, 0x84000
	s_addc_u32 s25, s25, 0
	global_load_lds_dwordx4 v136, s[26:27]
	s_add_i32 s26, s45, s0
	s_mov_b32 m0, s26
	s_nop 0
	global_load_lds_dwordx4 v132, s[24:25]
	s_add_i32 m0, s26, 0x2000
	s_nop 0
	global_load_lds_dwordx4 v136, s[24:25]
	s_mov_b32 m0, s35
	s_nop 0
	global_load_lds_dwordx4 v130, s[22:23]
	s_mov_b32 m0, s36
	s_nop 0
	global_load_lds_dwordx4 v134, s[22:23]
	s_waitcnt vmcnt(8)
	s_waitcnt lgkmcnt(0)
	s_setprio 1
	s_barrier
	v_mfma_f32_16x16x32_bf16 v[62:65], v[146:149], v[184:187], v[62:65]
	v_mfma_f32_16x16x32_bf16 v[62:65], v[156:159], v[188:191], v[62:65]
	v_mfma_f32_16x16x32_bf16 v[46:49], v[146:149], v[192:195], v[46:49]
	v_mfma_f32_16x16x32_bf16 v[46:49], v[156:159], v[196:199], v[46:49]
	v_mfma_f32_16x16x32_bf16 v[30:33], v[146:149], v[206:209], v[30:33]
	v_mfma_f32_16x16x32_bf16 v[30:33], v[156:159], v[212:215], v[30:33]
	v_mfma_f32_16x16x32_bf16 v[14:17], v[146:149], v[220:223], v[14:17]
	v_mfma_f32_16x16x32_bf16 v[14:17], v[156:159], v[224:227], v[14:17]
	v_mfma_f32_16x16x32_bf16 v[58:61], v[160:163], v[184:187], v[58:61]
	v_mfma_f32_16x16x32_bf16 v[58:61], v[164:167], v[188:191], v[58:61]
	v_mfma_f32_16x16x32_bf16 v[42:45], v[160:163], v[192:195], v[42:45]
	v_mfma_f32_16x16x32_bf16 v[42:45], v[164:167], v[196:199], v[42:45]
	v_mfma_f32_16x16x32_bf16 v[26:29], v[160:163], v[206:209], v[26:29]
	v_mfma_f32_16x16x32_bf16 v[26:29], v[164:167], v[212:215], v[26:29]
	v_mfma_f32_16x16x32_bf16 v[10:13], v[160:163], v[220:223], v[10:13]
	v_mfma_f32_16x16x32_bf16 v[10:13], v[164:167], v[224:227], v[10:13]
	s_setprio 0
	s_setprio 1
	v_mfma_f32_16x16x32_bf16 v[54:57], v[168:171], v[184:187], v[54:57]
	v_mfma_f32_16x16x32_bf16 v[54:57], v[172:175], v[188:191], v[54:57]
	v_mfma_f32_16x16x32_bf16 v[38:41], v[168:171], v[192:195], v[38:41]
	v_mfma_f32_16x16x32_bf16 v[38:41], v[172:175], v[196:199], v[38:41]
	v_mfma_f32_16x16x32_bf16 v[22:25], v[168:171], v[206:209], v[22:25]
	v_mfma_f32_16x16x32_bf16 v[22:25], v[172:175], v[212:215], v[22:25]
	v_mfma_f32_16x16x32_bf16 v[6:9], v[168:171], v[220:223], v[6:9]
	v_mfma_f32_16x16x32_bf16 v[6:9], v[172:175], v[224:227], v[6:9]
	v_mfma_f32_16x16x32_bf16 v[50:53], v[176:179], v[184:187], v[50:53]
	v_mfma_f32_16x16x32_bf16 v[50:53], v[180:183], v[188:191], v[50:53]
	v_mfma_f32_16x16x32_bf16 v[34:37], v[176:179], v[192:195], v[34:37]
	v_mfma_f32_16x16x32_bf16 v[34:37], v[180:183], v[196:199], v[34:37]
	v_mfma_f32_16x16x32_bf16 v[18:21], v[176:179], v[206:209], v[18:21]
	v_mfma_f32_16x16x32_bf16 v[18:21], v[180:183], v[212:215], v[18:21]
	v_mfma_f32_16x16x32_bf16 v[2:5], v[176:179], v[220:223], v[2:5]
	v_mfma_f32_16x16x32_bf16 v[2:5], v[180:183], v[224:227], v[2:5]
	s_barrier
	s_setprio 0
	s_add_i32 s43, s43, 2
	s_add_u32 s41, s41, 0x100000
	s_addc_u32 s42, s42, 0
	s_add_u32 s20, s20, 0x200000
	s_addc_u32 s21, s21, 0
	s_cmp_gt_u32 s43, 61
	s_cbranch_scc0 .LBB0_1217
	s_and_b64 vcc, exec, s[8:9]
	s_cbranch_vccz .LBB0_1220
	s_barrier

.LBB0_1670:
	ds_read_b128 v[148:151], v143
	ds_read_b128 v[152:155], v143 offset:1024
	ds_read_b128 v[156:159], v143 offset:2048
	ds_read_b128 v[160:163], v143 offset:3072
	s_add_u32 s10, s6, 0x4000
	s_addc_u32 s11, s7, 0
	s_cmp_eq_u32 s28, 60
	s_cselect_b32 s18, s14, s10
	s_cselect_b32 s19, s15, s11
	s_cselect_b32 s16, s4, s26
	s_cselect_b32 s17, s5, s27
	s_add_u32 s10, s18, 0x8000
	s_addc_u32 s11, s19, 0
	s_mov_b32 m0, s29
	ds_read_b128 v[180:183], v145
	ds_read_b128 v[184:187], v145 offset:1024
	ds_read_b128 v[188:191], v145 offset:2048
	ds_read_b128 v[192:195], v145 offset:3072
	ds_read_b128 v[196:199], v145 offset:4096
	ds_read_b128 v[206:209], v145 offset:5120
	ds_read_b128 v[212:215], v145 offset:6144
	ds_read_b128 v[220:223], v145 offset:7168
	global_load_lds_dwordx4 v138, s[6:7]
	s_mov_b32 m0, s30
	s_nop 0
	global_load_lds_dwordx4 v140, s[6:7]
	ds_read_b128 v[164:167], v144
	ds_read_b128 v[168:171], v144 offset:1024
	ds_read_b128 v[172:175], v144 offset:2048
	ds_read_b128 v[176:179], v144 offset:3072
	s_waitcnt vmcnt(8)
	s_waitcnt lgkmcnt(4)
	s_setprio 1
	s_barrier
	v_mfma_f32_16x16x32_bf16 v[126:129], v[148:151], v[180:183], v[126:129]
	v_mfma_f32_16x16x32_bf16 v[126:129], v[152:155], v[184:187], v[126:129]
	v_mfma_f32_16x16x32_bf16 v[118:121], v[148:151], v[188:191], v[118:121]
	v_mfma_f32_16x16x32_bf16 v[118:121], v[152:155], v[192:195], v[118:121]
	v_mfma_f32_16x16x32_bf16 v[102:105], v[148:151], v[196:199], v[102:105]
	v_mfma_f32_16x16x32_bf16 v[102:105], v[152:155], v[206:209], v[102:105]
	v_mfma_f32_16x16x32_bf16 v[86:89], v[148:151], v[212:215], v[86:89]
	v_mfma_f32_16x16x32_bf16 v[86:89], v[152:155], v[220:223], v[86:89]
	v_mfma_f32_16x16x32_bf16 v[122:125], v[156:159], v[180:183], v[122:125]
	v_mfma_f32_16x16x32_bf16 v[122:125], v[160:163], v[184:187], v[122:125]
	v_mfma_f32_16x16x32_bf16 v[110:113], v[156:159], v[188:191], v[110:113]
	v_mfma_f32_16x16x32_bf16 v[110:113], v[160:163], v[192:195], v[110:113]
	v_mfma_f32_16x16x32_bf16 v[94:97], v[156:159], v[196:199], v[94:97]
	v_mfma_f32_16x16x32_bf16 v[94:97], v[160:163], v[206:209], v[94:97]
	v_mfma_f32_16x16x32_bf16 v[78:81], v[156:159], v[212:215], v[78:81]
	v_mfma_f32_16x16x32_bf16 v[78:81], v[160:163], v[220:223], v[78:81]
	s_setprio 0
	s_waitcnt lgkmcnt(0)
	s_setprio 1
	v_mfma_f32_16x16x32_bf16 v[114:117], v[164:167], v[180:183], v[114:117]
	v_mfma_f32_16x16x32_bf16 v[114:117], v[168:171], v[184:187], v[114:117]
	v_mfma_f32_16x16x32_bf16 v[98:101], v[164:167], v[188:191], v[98:101]
	v_mfma_f32_16x16x32_bf16 v[98:101], v[168:171], v[192:195], v[98:101]
	v_mfma_f32_16x16x32_bf16 v[82:85], v[164:167], v[196:199], v[82:85]
	v_mfma_f32_16x16x32_bf16 v[82:85], v[168:171], v[206:209], v[82:85]
	v_mfma_f32_16x16x32_bf16 v[70:73], v[164:167], v[212:215], v[70:73]
	v_mfma_f32_16x16x32_bf16 v[70:73], v[168:171], v[220:223], v[70:73]
	v_mfma_f32_16x16x32_bf16 v[106:109], v[172:175], v[180:183], v[106:109]
	v_mfma_f32_16x16x32_bf16 v[106:109], v[176:179], v[184:187], v[106:109]
	v_mfma_f32_16x16x32_bf16 v[90:93], v[172:175], v[188:191], v[90:93]
	v_mfma_f32_16x16x32_bf16 v[90:93], v[176:179], v[192:195], v[90:93]
	v_mfma_f32_16x16x32_bf16 v[74:77], v[172:175], v[196:199], v[74:77]
	v_mfma_f32_16x16x32_bf16 v[74:77], v[176:179], v[206:209], v[74:77]
	v_mfma_f32_16x16x32_bf16 v[66:69], v[172:175], v[212:215], v[66:69]
	v_mfma_f32_16x16x32_bf16 v[66:69], v[176:179], v[220:223], v[66:69]
	s_barrier
	s_setprio 0
	s_mov_b32 m0, s31
	s_add_u32 s40, s16, 0x4000
	ds_read_b128 v[180:183], v145 offset:16384
	ds_read_b128 v[184:187], v145 offset:17408
	ds_read_b128 v[188:191], v145 offset:18432
	ds_read_b128 v[192:195], v145 offset:19456
	ds_read_b128 v[196:199], v145 offset:20480
	ds_read_b128 v[206:209], v145 offset:21504
	ds_read_b128 v[212:215], v145 offset:22528
	ds_read_b128 v[220:223], v145 offset:23552
	global_load_lds_dwordx4 v134, s[16:17]
	s_mov_b32 m0, s33
	s_addc_u32 s41, s17, 0
	global_load_lds_dwordx4 v130, s[16:17]
	s_mov_b32 m0, s34
	s_nop 0
	global_load_lds_dwordx4 v134, s[40:41]
	s_mov_b32 m0, s35
	s_nop 0
	global_load_lds_dwordx4 v130, s[40:41]
	s_mov_b32 m0, s1
	s_nop 0
	global_load_lds_dwordx4 v136, s[18:19]
	s_mov_b32 m0, s3
	s_nop 0
	global_load_lds_dwordx4 v132, s[18:19]
	s_waitcnt vmcnt(8)
	s_waitcnt lgkmcnt(0)
	s_setprio 1
	s_barrier
	v_mfma_f32_16x16x32_bf16 v[62:65], v[148:151], v[180:183], v[62:65]
	v_mfma_f32_16x16x32_bf16 v[62:65], v[152:155], v[184:187], v[62:65]
	v_mfma_f32_16x16x32_bf16 v[54:57], v[148:151], v[188:191], v[54:57]
	v_mfma_f32_16x16x32_bf16 v[54:57], v[152:155], v[192:195], v[54:57]
	v_mfma_f32_16x16x32_bf16 v[38:41], v[148:151], v[196:199], v[38:41]
	v_mfma_f32_16x16x32_bf16 v[38:41], v[152:155], v[206:209], v[38:41]
	v_mfma_f32_16x16x32_bf16 v[22:25], v[148:151], v[212:215], v[22:25]
	v_mfma_f32_16x16x32_bf16 v[22:25], v[152:155], v[220:223], v[22:25]
	v_mfma_f32_16x16x32_bf16 v[58:61], v[156:159], v[180:183], v[58:61]
	v_mfma_f32_16x16x32_bf16 v[58:61], v[160:163], v[184:187], v[58:61]
	v_mfma_f32_16x16x32_bf16 v[46:49], v[156:159], v[188:191], v[46:49]
	v_mfma_f32_16x16x32_bf16 v[46:49], v[160:163], v[192:195], v[46:49]
	v_mfma_f32_16x16x32_bf16 v[30:33], v[156:159], v[196:199], v[30:33]
	v_mfma_f32_16x16x32_bf16 v[30:33], v[160:163], v[206:209], v[30:33]
	v_mfma_f32_16x16x32_bf16 v[14:17], v[156:159], v[212:215], v[14:17]
	v_mfma_f32_16x16x32_bf16 v[14:17], v[160:163], v[220:223], v[14:17]
	s_setprio 0
	s_setprio 1
	v_mfma_f32_16x16x32_bf16 v[50:53], v[164:167], v[180:183], v[50:53]
	v_mfma_f32_16x16x32_bf16 v[50:53], v[168:171], v[184:187], v[50:53]
	v_mfma_f32_16x16x32_bf16 v[34:37], v[164:167], v[188:191], v[34:37]
	v_mfma_f32_16x16x32_bf16 v[34:37], v[168:171], v[192:195], v[34:37]
	v_mfma_f32_16x16x32_bf16 v[18:21], v[164:167], v[196:199], v[18:21]
	v_mfma_f32_16x16x32_bf16 v[18:21], v[168:171], v[206:209], v[18:21]
	v_mfma_f32_16x16x32_bf16 v[6:9], v[164:167], v[212:215], v[6:9]
	v_mfma_f32_16x16x32_bf16 v[6:9], v[168:171], v[220:223], v[6:9]
	v_mfma_f32_16x16x32_bf16 v[42:45], v[172:175], v[180:183], v[42:45]
	v_mfma_f32_16x16x32_bf16 v[42:45], v[176:179], v[184:187], v[42:45]
	v_mfma_f32_16x16x32_bf16 v[26:29], v[172:175], v[188:191], v[26:29]
	v_mfma_f32_16x16x32_bf16 v[26:29], v[176:179], v[192:195], v[26:29]
	v_mfma_f32_16x16x32_bf16 v[10:13], v[172:175], v[196:199], v[10:13]
	v_mfma_f32_16x16x32_bf16 v[10:13], v[176:179], v[206:209], v[10:13]
	v_mfma_f32_16x16x32_bf16 v[2:5], v[172:175], v[212:215], v[2:5]
	v_mfma_f32_16x16x32_bf16 v[2:5], v[176:179], v[220:223], v[2:5]
	s_barrier
	s_setprio 0
	ds_read_b128 v[148:151], v146
	ds_read_b128 v[152:155], v146 offset:1024
	ds_read_b128 v[156:159], v146 offset:2048
	ds_read_b128 v[160:163], v146 offset:3072
	s_add_u32 s18, s18, 0x4000
	s_addc_u32 s19, s19, 0
	s_mov_b32 m0, s20
	ds_read_b128 v[180:183], v145 offset:32768
	ds_read_b128 v[184:187], v145 offset:33792
	ds_read_b128 v[188:191], v145 offset:34816
	ds_read_b128 v[192:195], v145 offset:35840
	ds_read_b128 v[196:199], v145 offset:36864
	ds_read_b128 v[206:209], v145 offset:37888
	ds_read_b128 v[212:215], v145 offset:38912
	ds_read_b128 v[220:223], v145 offset:39936
	global_load_lds_dwordx4 v136, s[18:19]
	s_mov_b32 m0, s21
	s_nop 0
	global_load_lds_dwordx4 v132, s[18:19]
	ds_read_b128 v[164:167], v147
	ds_read_b128 v[168:171], v147 offset:1024
	ds_read_b128 v[172:175], v147 offset:2048
	ds_read_b128 v[176:179], v147 offset:3072
	s_waitcnt vmcnt(8)
	s_waitcnt lgkmcnt(4)
	s_setprio 1
	s_barrier
	v_mfma_f32_16x16x32_bf16 v[126:129], v[148:151], v[180:183], v[126:129]
	v_mfma_f32_16x16x32_bf16 v[126:129], v[152:155], v[184:187], v[126:129]
	v_mfma_f32_16x16x32_bf16 v[118:121], v[148:151], v[188:191], v[118:121]
	v_mfma_f32_16x16x32_bf16 v[118:121], v[152:155], v[192:195], v[118:121]
	v_mfma_f32_16x16x32_bf16 v[102:105], v[148:151], v[196:199], v[102:105]
	v_mfma_f32_16x16x32_bf16 v[102:105], v[152:155], v[206:209], v[102:105]
	v_mfma_f32_16x16x32_bf16 v[86:89], v[148:151], v[212:215], v[86:89]
	v_mfma_f32_16x16x32_bf16 v[86:89], v[152:155], v[220:223], v[86:89]
	v_mfma_f32_16x16x32_bf16 v[122:125], v[156:159], v[180:183], v[122:125]
	v_mfma_f32_16x16x32_bf16 v[122:125], v[160:163], v[184:187], v[122:125]
	v_mfma_f32_16x16x32_bf16 v[110:113], v[156:159], v[188:191], v[110:113]
	v_mfma_f32_16x16x32_bf16 v[110:113], v[160:163], v[192:195], v[110:113]
	v_mfma_f32_16x16x32_bf16 v[94:97], v[156:159], v[196:199], v[94:97]
	v_mfma_f32_16x16x32_bf16 v[94:97], v[160:163], v[206:209], v[94:97]
	v_mfma_f32_16x16x32_bf16 v[78:81], v[156:159], v[212:215], v[78:81]
	v_mfma_f32_16x16x32_bf16 v[78:81], v[160:163], v[220:223], v[78:81]
	s_setprio 0
	s_waitcnt lgkmcnt(0)
	s_setprio 1
	v_mfma_f32_16x16x32_bf16 v[114:117], v[164:167], v[180:183], v[114:117]
	v_mfma_f32_16x16x32_bf16 v[114:117], v[168:171], v[184:187], v[114:117]
	v_mfma_f32_16x16x32_bf16 v[98:101], v[164:167], v[188:191], v[98:101]
	v_mfma_f32_16x16x32_bf16 v[98:101], v[168:171], v[192:195], v[98:101]
	v_mfma_f32_16x16x32_bf16 v[82:85], v[164:167], v[196:199], v[82:85]
	v_mfma_f32_16x16x32_bf16 v[82:85], v[168:171], v[206:209], v[82:85]
	v_mfma_f32_16x16x32_bf16 v[70:73], v[164:167], v[212:215], v[70:73]
	v_mfma_f32_16x16x32_bf16 v[70:73], v[168:171], v[220:223], v[70:73]
	v_mfma_f32_16x16x32_bf16 v[106:109], v[172:175], v[180:183], v[106:109]
	v_mfma_f32_16x16x32_bf16 v[106:109], v[176:179], v[184:187], v[106:109]
	v_mfma_f32_16x16x32_bf16 v[90:93], v[172:175], v[188:191], v[90:93]
	v_mfma_f32_16x16x32_bf16 v[90:93], v[176:179], v[192:195], v[90:93]
	v_mfma_f32_16x16x32_bf16 v[74:77], v[172:175], v[196:199], v[74:77]
	v_mfma_f32_16x16x32_bf16 v[74:77], v[176:179], v[206:209], v[74:77]
	v_mfma_f32_16x16x32_bf16 v[66:69], v[172:175], v[212:215], v[66:69]
	v_mfma_f32_16x16x32_bf16 v[66:69], v[176:179], v[220:223], v[66:69]
	s_barrier
	s_setprio 0
	s_add_u32 s18, s16, 0x20000
	s_addc_u32 s19, s17, 0
	s_mov_b32 m0, s36
	s_add_u32 s16, s16, 0x24000
	ds_read_b128 v[180:183], v145 offset:49152
	ds_read_b128 v[184:187], v145 offset:50176
	ds_read_b128 v[188:191], v145 offset:51200
	ds_read_b128 v[192:195], v145 offset:52224
	ds_read_b128 v[196:199], v145 offset:53248
	ds_read_b128 v[206:209], v145 offset:54272
	ds_read_b128 v[212:215], v145 offset:55296
	ds_read_b128 v[220:223], v145 offset:56320
	global_load_lds_dwordx4 v134, s[18:19]
	s_mov_b32 m0, s37
	s_addc_u32 s17, s17, 0
	global_load_lds_dwordx4 v130, s[18:19]
	s_mov_b32 m0, s38
	s_nop 0
	global_load_lds_dwordx4 v134, s[16:17]
	s_mov_b32 m0, s39
	s_nop 0
	global_load_lds_dwordx4 v130, s[16:17]
	s_mov_b32 m0, s24
	s_nop 0
	global_load_lds_dwordx4 v136, s[10:11]
	s_mov_b32 m0, s25
	s_nop 0
	global_load_lds_dwordx4 v132, s[10:11]
	s_waitcnt vmcnt(8)
	s_waitcnt lgkmcnt(0)
	s_setprio 1
	s_barrier
	v_mfma_f32_16x16x32_bf16 v[62:65], v[148:151], v[180:183], v[62:65]
	v_mfma_f32_16x16x32_bf16 v[62:65], v[152:155], v[184:187], v[62:65]
	v_mfma_f32_16x16x32_bf16 v[54:57], v[148:151], v[188:191], v[54:57]
	v_mfma_f32_16x16x32_bf16 v[54:57], v[152:155], v[192:195], v[54:57]
	v_mfma_f32_16x16x32_bf16 v[38:41], v[148:151], v[196:199], v[38:41]
	v_mfma_f32_16x16x32_bf16 v[38:41], v[152:155], v[206:209], v[38:41]
	v_mfma_f32_16x16x32_bf16 v[22:25], v[148:151], v[212:215], v[22:25]
	v_mfma_f32_16x16x32_bf16 v[22:25], v[152:155], v[220:223], v[22:25]
	v_mfma_f32_16x16x32_bf16 v[58:61], v[156:159], v[180:183], v[58:61]
	v_mfma_f32_16x16x32_bf16 v[58:61], v[160:163], v[184:187], v[58:61]
	v_mfma_f32_16x16x32_bf16 v[46:49], v[156:159], v[188:191], v[46:49]
	v_mfma_f32_16x16x32_bf16 v[46:49], v[160:163], v[192:195], v[46:49]
	v_mfma_f32_16x16x32_bf16 v[30:33], v[156:159], v[196:199], v[30:33]
	v_mfma_f32_16x16x32_bf16 v[30:33], v[160:163], v[206:209], v[30:33]
	v_mfma_f32_16x16x32_bf16 v[14:17], v[156:159], v[212:215], v[14:17]
	v_mfma_f32_16x16x32_bf16 v[14:17], v[160:163], v[220:223], v[14:17]
	s_setprio 0
	s_setprio 1
	v_mfma_f32_16x16x32_bf16 v[50:53], v[164:167], v[180:183], v[50:53]
	v_mfma_f32_16x16x32_bf16 v[50:53], v[168:171], v[184:187], v[50:53]
	v_mfma_f32_16x16x32_bf16 v[34:37], v[164:167], v[188:191], v[34:37]
	v_mfma_f32_16x16x32_bf16 v[34:37], v[168:171], v[192:195], v[34:37]
	v_mfma_f32_16x16x32_bf16 v[18:21], v[164:167], v[196:199], v[18:21]
	v_mfma_f32_16x16x32_bf16 v[18:21], v[168:171], v[206:209], v[18:21]
	v_mfma_f32_16x16x32_bf16 v[6:9], v[164:167], v[212:215], v[6:9]
	v_mfma_f32_16x16x32_bf16 v[6:9], v[168:171], v[220:223], v[6:9]
	v_mfma_f32_16x16x32_bf16 v[42:45], v[172:175], v[180:183], v[42:45]
	v_mfma_f32_16x16x32_bf16 v[42:45], v[176:179], v[184:187], v[42:45]
	v_mfma_f32_16x16x32_bf16 v[26:29], v[172:175], v[188:191], v[26:29]
	v_mfma_f32_16x16x32_bf16 v[26:29], v[176:179], v[192:195], v[26:29]
	v_mfma_f32_16x16x32_bf16 v[10:13], v[172:175], v[196:199], v[10:13]
	v_mfma_f32_16x16x32_bf16 v[10:13], v[176:179], v[206:209], v[10:13]
	v_mfma_f32_16x16x32_bf16 v[2:5], v[172:175], v[212:215], v[2:5]
	v_mfma_f32_16x16x32_bf16 v[2:5], v[176:179], v[220:223], v[2:5]
	s_barrier
	s_setprio 0
	s_add_i32 s28, s28, 2
	s_add_u32 s26, s26, 0x40000
	s_addc_u32 s27, s27, 0
	s_add_u32 s6, s6, 0x10000
	s_addc_u32 s7, s7, 0
	s_cmp_gt_u32 s28, 61
	s_cbranch_scc0 .LBB0_1670
	s_lshl_b32 s1, s2, 8
	v_and_or_b32 v132, v142, 15, s22
	v_lshrrev_b32_e32 v130, 1, v142
	v_and_or_b32 v130, v130, 24, s1
	v_ashrrev_i32_e32 v133, 31, v132
	v_or_b32_e32 v134, s23, v130
	v_lshlrev_b64 v[130:131], 11, v[132:133]
	v_lshl_add_u64 v[130:131], s[8:9], 0, v[130:131]
	v_lshlrev_b32_e32 v134, 1, v134
	v_mov_b32_e32 v135, 0
	v_lshl_add_u64 v[130:131], v[130:131], 0, v[134:135]
	v_cvt_pk_bf16_f32 v126, v126, v127
	v_cvt_pk_bf16_f32 v127, v128, v129
	v_cvt_pk_bf16_f32 v128, v122, v123
	v_cvt_pk_bf16_f32 v129, v124, v125
	global_store_dwordx4 v[130:131], v[126:129], off
	v_cvt_pk_bf16_f32 v114, v114, v115
	v_cvt_pk_bf16_f32 v115, v116, v117
	v_cvt_pk_bf16_f32 v116, v106, v107
	v_or_b32_e32 v106, 16, v132
	v_ashrrev_i32_e32 v107, 31, v106
	v_lshlrev_b64 v[106:107], 11, v[106:107]
	v_lshl_add_u64 v[106:107], s[8:9], 0, v[106:107]
	v_cvt_pk_bf16_f32 v117, v108, v109
	global_store_dwordx4 v[130:131], v[114:117], off offset:256
	s_mov_b32 s1, 0x40000
	s_mov_b64 s[2:3], 0x40000
	v_lshl_add_u64 v[114:115], v[106:107], 0, v[134:135]
	v_cvt_pk_bf16_f32 v106, v118, v119
	v_cvt_pk_bf16_f32 v107, v120, v121
	v_cvt_pk_bf16_f32 v108, v110, v111
	v_cvt_pk_bf16_f32 v109, v112, v113
	global_store_dwordx4 v[114:115], v[106:109], off
	v_cvt_pk_bf16_f32 v98, v98, v99
	v_cvt_pk_bf16_f32 v99, v100, v101
	v_cvt_pk_bf16_f32 v100, v90, v91
	v_or_b32_e32 v90, 32, v132
	v_ashrrev_i32_e32 v91, 31, v90
	v_lshlrev_b64 v[90:91], 11, v[90:91]
	v_lshl_add_u64 v[90:91], s[8:9], 0, v[90:91]
	v_cvt_pk_bf16_f32 v101, v92, v93
	global_store_dwordx4 v[114:115], v[98:101], off offset:256
	s_cmpk_lt_u32 s0, 0x100
	s_nop 0
	v_lshl_add_u64 v[98:99], v[90:91], 0, v[134:135]
	v_cvt_pk_bf16_f32 v90, v102, v103
	v_cvt_pk_bf16_f32 v91, v104, v105
	v_cvt_pk_bf16_f32 v92, v94, v95
	v_cvt_pk_bf16_f32 v93, v96, v97
	global_store_dwordx4 v[98:99], v[90:93], off
	v_cvt_pk_bf16_f32 v82, v82, v83
	v_cvt_pk_bf16_f32 v83, v84, v85
	v_cvt_pk_bf16_f32 v84, v74, v75
	v_or_b32_e32 v74, 48, v132
	v_ashrrev_i32_e32 v75, 31, v74
	v_lshlrev_b64 v[74:75], 11, v[74:75]
	v_lshl_add_u64 v[74:75], s[8:9], 0, v[74:75]
	v_cvt_pk_bf16_f32 v85, v76, v77
	global_store_dwordx4 v[98:99], v[82:85], off offset:256
	s_nop 1
	v_lshl_add_u64 v[82:83], v[74:75], 0, v[134:135]
	v_cvt_pk_bf16_f32 v74, v86, v87
	v_cvt_pk_bf16_f32 v75, v88, v89
	v_cvt_pk_bf16_f32 v76, v78, v79
	v_cvt_pk_bf16_f32 v77, v80, v81
	global_store_dwordx4 v[82:83], v[74:77], off
	v_cvt_pk_bf16_f32 v70, v70, v71
	v_cvt_pk_bf16_f32 v71, v72, v73
	v_cvt_pk_bf16_f32 v72, v66, v67
	v_cvt_pk_bf16_f32 v73, v68, v69
	global_store_dwordx4 v[82:83], v[70:73], off offset:256
	v_cvt_pk_bf16_f32 v62, v62, v63
	v_cvt_pk_bf16_f32 v63, v64, v65
	v_cvt_pk_bf16_f32 v64, v58, v59
	v_add_co_u32_e32 v58, vcc, s1, v130
	v_lshl_add_u64 v[66:67], v[130:131], 0, s[2:3]
	s_nop 0
	v_addc_co_u32_e32 v59, vcc, 0, v131, vcc
	s_mov_b32 s1, 0x48000
	v_cvt_pk_bf16_f32 v65, v60, v61
	global_store_dwordx4 v[58:59], v[62:65], off
	v_cvt_pk_bf16_f32 v50, v50, v51
	v_cvt_pk_bf16_f32 v51, v52, v53
	v_cvt_pk_bf16_f32 v52, v42, v43
	v_cvt_pk_bf16_f32 v53, v44, v45
	global_store_dwordx4 v[66:67], v[50:53], off offset:256
	s_mov_b64 s[2:3], 0x48000
	v_cvt_pk_bf16_f32 v42, v54, v55
	v_cvt_pk_bf16_f32 v43, v56, v57
	v_cvt_pk_bf16_f32 v44, v46, v47
	v_add_co_u32_e32 v46, vcc, s1, v130
	v_lshl_add_u64 v[50:51], v[130:131], 0, s[2:3]
	s_nop 0
	v_addc_co_u32_e32 v47, vcc, 0, v131, vcc
	s_mov_b32 s1, 0x50000
	v_cvt_pk_bf16_f32 v45, v48, v49
	global_store_dwordx4 v[46:47], v[42:45], off
	v_cvt_pk_bf16_f32 v34, v34, v35
	v_cvt_pk_bf16_f32 v35, v36, v37
	v_cvt_pk_bf16_f32 v36, v26, v27
	v_cvt_pk_bf16_f32 v37, v28, v29
	global_store_dwordx4 v[50:51], v[34:37], off offset:256
	s_mov_b64 s[2:3], 0x50000
	v_cvt_pk_bf16_f32 v26, v38, v39
	v_cvt_pk_bf16_f32 v27, v40, v41
	v_cvt_pk_bf16_f32 v28, v30, v31
	v_add_co_u32_e32 v30, vcc, s1, v130
	v_lshl_add_u64 v[34:35], v[130:131], 0, s[2:3]
	s_nop 0
	v_addc_co_u32_e32 v31, vcc, 0, v131, vcc
	s_mov_b32 s1, 0x58000
	v_cvt_pk_bf16_f32 v29, v32, v33
	global_store_dwordx4 v[30:31], v[26:29], off
	v_cvt_pk_bf16_f32 v18, v18, v19
	v_cvt_pk_bf16_f32 v19, v20, v21
	v_cvt_pk_bf16_f32 v20, v10, v11
	v_cvt_pk_bf16_f32 v21, v12, v13
	global_store_dwordx4 v[34:35], v[18:21], off offset:256
	s_mov_b64 s[2:3], 0x58000
	v_cvt_pk_bf16_f32 v10, v22, v23
	v_cvt_pk_bf16_f32 v11, v24, v25
	v_cvt_pk_bf16_f32 v12, v14, v15
	v_add_co_u32_e32 v14, vcc, s1, v130
	v_lshl_add_u64 v[18:19], v[130:131], 0, s[2:3]
	s_nop 0
	v_addc_co_u32_e32 v15, vcc, 0, v131, vcc
	v_cvt_pk_bf16_f32 v13, v16, v17
	global_store_dwordx4 v[14:15], v[10:13], off
	v_cvt_pk_bf16_f32 v6, v6, v7
	v_cvt_pk_bf16_f32 v7, v8, v9
	v_cvt_pk_bf16_f32 v8, v2, v3
	v_cvt_pk_bf16_f32 v9, v4, v5
	global_store_dwordx4 v[18:19], v[6:9], off offset:256
	s_waitcnt vmcnt(0)
	s_cbranch_scc0 .LBB0_1673
	s_barrier

.LBB0_1691:
	ds_read_b128 v[142:145], v150
	ds_read_b128 v[154:157], v150 offset:1024
	ds_read_b128 v[158:161], v150 offset:2048
	ds_read_b128 v[162:165], v150 offset:3072
	s_add_u32 s24, s22, 0xfc000
	s_addc_u32 s25, s23, 0
	s_cmp_eq_u32 s46, 60
	s_cselect_b32 s28, s17, s24
	s_cselect_b32 s29, s11, s25
	s_cselect_b32 s26, s43, s44
	s_cselect_b32 s27, s7, s45
	s_add_u32 s24, s28, 0x100000
	s_addc_u32 s25, s29, 0
	s_add_i32 m0, s30, 0xc000
	ds_read_b128 v[182:185], v152
	ds_read_b128 v[186:189], v152 offset:1024
	ds_read_b128 v[190:193], v152 offset:2048
	ds_read_b128 v[194:197], v152 offset:3072
	ds_read_b128 v[206:209], v152 offset:4096
	ds_read_b128 v[212:215], v152 offset:5120
	ds_read_b128 v[220:223], v152 offset:6144
	ds_read_b128 v[224:227], v152 offset:7168
	global_load_lds_dwordx4 v138, s[22:23]
	s_add_i32 m0, s30, 0xe000
	s_nop 0
	global_load_lds_dwordx4 v140, s[22:23]
	ds_read_b128 v[166:169], v151
	ds_read_b128 v[170:173], v151 offset:1024
	ds_read_b128 v[174:177], v151 offset:2048
	ds_read_b128 v[178:181], v151 offset:3072
	s_waitcnt vmcnt(8)
	s_waitcnt lgkmcnt(4)
	s_setprio 1
	s_barrier
	v_mfma_f32_16x16x32_bf16 v[126:129], v[142:145], v[182:185], v[126:129]
	v_mfma_f32_16x16x32_bf16 v[126:129], v[154:157], v[186:189], v[126:129]
	v_mfma_f32_16x16x32_bf16 v[110:113], v[142:145], v[190:193], v[110:113]
	v_mfma_f32_16x16x32_bf16 v[110:113], v[154:157], v[194:197], v[110:113]
	v_mfma_f32_16x16x32_bf16 v[94:97], v[142:145], v[206:209], v[94:97]
	v_mfma_f32_16x16x32_bf16 v[94:97], v[154:157], v[212:215], v[94:97]
	v_mfma_f32_16x16x32_bf16 v[78:81], v[142:145], v[220:223], v[78:81]
	v_mfma_f32_16x16x32_bf16 v[78:81], v[154:157], v[224:227], v[78:81]
	v_mfma_f32_16x16x32_bf16 v[122:125], v[158:161], v[182:185], v[122:125]
	v_mfma_f32_16x16x32_bf16 v[122:125], v[162:165], v[186:189], v[122:125]
	v_mfma_f32_16x16x32_bf16 v[106:109], v[158:161], v[190:193], v[106:109]
	v_mfma_f32_16x16x32_bf16 v[106:109], v[162:165], v[194:197], v[106:109]
	v_mfma_f32_16x16x32_bf16 v[90:93], v[158:161], v[206:209], v[90:93]
	v_mfma_f32_16x16x32_bf16 v[90:93], v[162:165], v[212:215], v[90:93]
	v_mfma_f32_16x16x32_bf16 v[74:77], v[158:161], v[220:223], v[74:77]
	v_mfma_f32_16x16x32_bf16 v[74:77], v[162:165], v[224:227], v[74:77]
	s_setprio 0
	s_waitcnt lgkmcnt(0)
	s_setprio 1
	v_mfma_f32_16x16x32_bf16 v[118:121], v[166:169], v[182:185], v[118:121]
	v_mfma_f32_16x16x32_bf16 v[118:121], v[170:173], v[186:189], v[118:121]
	v_mfma_f32_16x16x32_bf16 v[102:105], v[166:169], v[190:193], v[102:105]
	v_mfma_f32_16x16x32_bf16 v[102:105], v[170:173], v[194:197], v[102:105]
	v_mfma_f32_16x16x32_bf16 v[86:89], v[166:169], v[206:209], v[86:89]
	v_mfma_f32_16x16x32_bf16 v[86:89], v[170:173], v[212:215], v[86:89]
	v_mfma_f32_16x16x32_bf16 v[70:73], v[166:169], v[220:223], v[70:73]
	v_mfma_f32_16x16x32_bf16 v[70:73], v[170:173], v[224:227], v[70:73]
	v_mfma_f32_16x16x32_bf16 v[114:117], v[174:177], v[182:185], v[114:117]
	v_mfma_f32_16x16x32_bf16 v[114:117], v[178:181], v[186:189], v[114:117]
	v_mfma_f32_16x16x32_bf16 v[98:101], v[174:177], v[190:193], v[98:101]
	v_mfma_f32_16x16x32_bf16 v[98:101], v[178:181], v[194:197], v[98:101]
	v_mfma_f32_16x16x32_bf16 v[82:85], v[174:177], v[206:209], v[82:85]
	v_mfma_f32_16x16x32_bf16 v[82:85], v[178:181], v[212:215], v[82:85]
	v_mfma_f32_16x16x32_bf16 v[66:69], v[174:177], v[220:223], v[66:69]
	v_mfma_f32_16x16x32_bf16 v[66:69], v[178:181], v[224:227], v[66:69]
	s_barrier
	s_setprio 0
	s_add_i32 s47, s40, s1
	s_mov_b32 m0, s47
	ds_read_b128 v[182:185], v152 offset:16384
	ds_read_b128 v[186:189], v152 offset:17408
	ds_read_b128 v[190:193], v152 offset:18432
	ds_read_b128 v[194:197], v152 offset:19456
	ds_read_b128 v[206:209], v152 offset:20480
	ds_read_b128 v[212:215], v152 offset:21504
	ds_read_b128 v[220:223], v152 offset:22528
	ds_read_b128 v[224:227], v152 offset:23552
	global_load_lds_dwordx4 v132, s[26:27]
	s_add_i32 m0, s47, 0x2000
	s_add_u32 s48, s26, 0x4000
	s_addc_u32 s49, s27, 0
	s_add_i32 s47, s41, s1
	global_load_lds_dwordx4 v136, s[26:27]
	s_mov_b32 m0, s47
	s_nop 0
	global_load_lds_dwordx4 v132, s[48:49]
	s_add_i32 m0, s47, 0x2000
	s_nop 0
	global_load_lds_dwordx4 v136, s[48:49]
	s_mov_b32 m0, s30
	s_nop 0
	global_load_lds_dwordx4 v130, s[28:29]
	s_mov_b32 m0, s31
	s_nop 0
	global_load_lds_dwordx4 v134, s[28:29]
	s_waitcnt vmcnt(8)
	s_waitcnt lgkmcnt(0)
	s_setprio 1
	s_barrier
	v_mfma_f32_16x16x32_bf16 v[62:65], v[142:145], v[182:185], v[62:65]
	v_mfma_f32_16x16x32_bf16 v[62:65], v[154:157], v[186:189], v[62:65]
	v_mfma_f32_16x16x32_bf16 v[46:49], v[142:145], v[190:193], v[46:49]
	v_mfma_f32_16x16x32_bf16 v[46:49], v[154:157], v[194:197], v[46:49]
	v_mfma_f32_16x16x32_bf16 v[30:33], v[142:145], v[206:209], v[30:33]
	v_mfma_f32_16x16x32_bf16 v[30:33], v[154:157], v[212:215], v[30:33]
	v_mfma_f32_16x16x32_bf16 v[14:17], v[142:145], v[220:223], v[14:17]
	v_mfma_f32_16x16x32_bf16 v[14:17], v[154:157], v[224:227], v[14:17]
	v_mfma_f32_16x16x32_bf16 v[58:61], v[158:161], v[182:185], v[58:61]
	v_mfma_f32_16x16x32_bf16 v[58:61], v[162:165], v[186:189], v[58:61]
	v_mfma_f32_16x16x32_bf16 v[42:45], v[158:161], v[190:193], v[42:45]
	v_mfma_f32_16x16x32_bf16 v[42:45], v[162:165], v[194:197], v[42:45]
	v_mfma_f32_16x16x32_bf16 v[26:29], v[158:161], v[206:209], v[26:29]
	v_mfma_f32_16x16x32_bf16 v[26:29], v[162:165], v[212:215], v[26:29]
	v_mfma_f32_16x16x32_bf16 v[10:13], v[158:161], v[220:223], v[10:13]
	v_mfma_f32_16x16x32_bf16 v[10:13], v[162:165], v[224:227], v[10:13]
	s_setprio 0
	s_setprio 1
	v_mfma_f32_16x16x32_bf16 v[54:57], v[166:169], v[182:185], v[54:57]
	v_mfma_f32_16x16x32_bf16 v[54:57], v[170:173], v[186:189], v[54:57]
	v_mfma_f32_16x16x32_bf16 v[38:41], v[166:169], v[190:193], v[38:41]
	v_mfma_f32_16x16x32_bf16 v[38:41], v[170:173], v[194:197], v[38:41]
	v_mfma_f32_16x16x32_bf16 v[22:25], v[166:169], v[206:209], v[22:25]
	v_mfma_f32_16x16x32_bf16 v[22:25], v[170:173], v[212:215], v[22:25]
	v_mfma_f32_16x16x32_bf16 v[6:9], v[166:169], v[220:223], v[6:9]
	v_mfma_f32_16x16x32_bf16 v[6:9], v[170:173], v[224:227], v[6:9]
	v_mfma_f32_16x16x32_bf16 v[50:53], v[174:177], v[182:185], v[50:53]
	v_mfma_f32_16x16x32_bf16 v[50:53], v[178:181], v[186:189], v[50:53]
	v_mfma_f32_16x16x32_bf16 v[34:37], v[174:177], v[190:193], v[34:37]
	v_mfma_f32_16x16x32_bf16 v[34:37], v[178:181], v[194:197], v[34:37]
	v_mfma_f32_16x16x32_bf16 v[18:21], v[174:177], v[206:209], v[18:21]
	v_mfma_f32_16x16x32_bf16 v[18:21], v[178:181], v[212:215], v[18:21]
	v_mfma_f32_16x16x32_bf16 v[2:5], v[174:177], v[220:223], v[2:5]
	v_mfma_f32_16x16x32_bf16 v[2:5], v[178:181], v[224:227], v[2:5]
	s_barrier
	s_setprio 0
	s_add_i32 s47, 0, 0x18000
	v_add_u32_e32 v146, s47, v149
	s_add_i32 s48, 0, 0x1c000
	ds_read_b128 v[142:145], v146
	ds_read_b128 v[154:157], v146 offset:1024
	ds_read_b128 v[158:161], v146 offset:2048
	ds_read_b128 v[162:165], v146 offset:3072
	v_add_u32_e32 v146, s48, v149
	s_add_u32 s28, s28, 0x4000
	s_addc_u32 s29, s29, 0
	s_mov_b32 m0, s33
	ds_read_b128 v[182:185], v152 offset:32768
	ds_read_b128 v[186:189], v152 offset:33792
	ds_read_b128 v[190:193], v152 offset:34816
	ds_read_b128 v[194:197], v152 offset:35840
	ds_read_b128 v[206:209], v152 offset:36864
	ds_read_b128 v[212:215], v152 offset:37888
	ds_read_b128 v[220:223], v152 offset:38912
	ds_read_b128 v[224:227], v152 offset:39936
	global_load_lds_dwordx4 v130, s[28:29]
	s_mov_b32 m0, s34
	s_nop 0
	global_load_lds_dwordx4 v134, s[28:29]
	ds_read_b128 v[166:169], v146
	ds_read_b128 v[170:173], v146 offset:1024
	ds_read_b128 v[174:177], v146 offset:2048
	ds_read_b128 v[178:181], v146 offset:3072
	s_waitcnt vmcnt(8)
	s_waitcnt lgkmcnt(4)
	s_setprio 1
	s_barrier
	v_mfma_f32_16x16x32_bf16 v[126:129], v[142:145], v[182:185], v[126:129]
	v_mfma_f32_16x16x32_bf16 v[126:129], v[154:157], v[186:189], v[126:129]
	v_mfma_f32_16x16x32_bf16 v[110:113], v[142:145], v[190:193], v[110:113]
	v_mfma_f32_16x16x32_bf16 v[110:113], v[154:157], v[194:197], v[110:113]
	v_mfma_f32_16x16x32_bf16 v[94:97], v[142:145], v[206:209], v[94:97]
	v_mfma_f32_16x16x32_bf16 v[94:97], v[154:157], v[212:215], v[94:97]
	v_mfma_f32_16x16x32_bf16 v[78:81], v[142:145], v[220:223], v[78:81]
	v_mfma_f32_16x16x32_bf16 v[78:81], v[154:157], v[224:227], v[78:81]
	v_mfma_f32_16x16x32_bf16 v[122:125], v[158:161], v[182:185], v[122:125]
	v_mfma_f32_16x16x32_bf16 v[122:125], v[162:165], v[186:189], v[122:125]
	v_mfma_f32_16x16x32_bf16 v[106:109], v[158:161], v[190:193], v[106:109]
	v_mfma_f32_16x16x32_bf16 v[106:109], v[162:165], v[194:197], v[106:109]
	v_mfma_f32_16x16x32_bf16 v[90:93], v[158:161], v[206:209], v[90:93]
	v_mfma_f32_16x16x32_bf16 v[90:93], v[162:165], v[212:215], v[90:93]
	v_mfma_f32_16x16x32_bf16 v[74:77], v[158:161], v[220:223], v[74:77]
	v_mfma_f32_16x16x32_bf16 v[74:77], v[162:165], v[224:227], v[74:77]
	s_setprio 0
	s_waitcnt lgkmcnt(0)
	s_setprio 1
	v_mfma_f32_16x16x32_bf16 v[118:121], v[166:169], v[182:185], v[118:121]
	v_mfma_f32_16x16x32_bf16 v[118:121], v[170:173], v[186:189], v[118:121]
	v_mfma_f32_16x16x32_bf16 v[102:105], v[166:169], v[190:193], v[102:105]
	v_mfma_f32_16x16x32_bf16 v[102:105], v[170:173], v[194:197], v[102:105]
	v_mfma_f32_16x16x32_bf16 v[86:89], v[166:169], v[206:209], v[86:89]
	v_mfma_f32_16x16x32_bf16 v[86:89], v[170:173], v[212:215], v[86:89]
	v_mfma_f32_16x16x32_bf16 v[70:73], v[166:169], v[220:223], v[70:73]
	v_mfma_f32_16x16x32_bf16 v[70:73], v[170:173], v[224:227], v[70:73]
	v_mfma_f32_16x16x32_bf16 v[114:117], v[174:177], v[182:185], v[114:117]
	v_mfma_f32_16x16x32_bf16 v[114:117], v[178:181], v[186:189], v[114:117]
	v_mfma_f32_16x16x32_bf16 v[98:101], v[174:177], v[190:193], v[98:101]
	v_mfma_f32_16x16x32_bf16 v[98:101], v[178:181], v[194:197], v[98:101]
	v_mfma_f32_16x16x32_bf16 v[82:85], v[174:177], v[206:209], v[82:85]
	v_mfma_f32_16x16x32_bf16 v[82:85], v[178:181], v[212:215], v[82:85]
	v_mfma_f32_16x16x32_bf16 v[66:69], v[174:177], v[220:223], v[66:69]
	v_mfma_f32_16x16x32_bf16 v[66:69], v[178:181], v[224:227], v[66:69]
	s_barrier
	s_setprio 0
	s_add_u32 s28, s26, 0x10000
	s_addc_u32 s29, s27, 0
	s_add_i32 s47, s47, s1
	s_mov_b32 m0, s47
	ds_read_b128 v[182:185], v152 offset:49152
	ds_read_b128 v[186:189], v152 offset:50176
	ds_read_b128 v[190:193], v152 offset:51200
	ds_read_b128 v[194:197], v152 offset:52224
	ds_read_b128 v[206:209], v152 offset:53248
	ds_read_b128 v[212:215], v152 offset:54272
	ds_read_b128 v[220:223], v152 offset:55296
	ds_read_b128 v[224:227], v152 offset:56320
	global_load_lds_dwordx4 v132, s[28:29]
	s_add_i32 m0, s47, 0x2000
	s_add_u32 s26, s26, 0x14000
	s_addc_u32 s27, s27, 0
	global_load_lds_dwordx4 v136, s[28:29]
	s_add_i32 s28, s48, s1
	s_mov_b32 m0, s28
	s_nop 0
	global_load_lds_dwordx4 v132, s[26:27]
	s_add_i32 m0, s28, 0x2000
	s_nop 0
	global_load_lds_dwordx4 v136, s[26:27]
	s_mov_b32 m0, s38
	s_nop 0
	global_load_lds_dwordx4 v130, s[24:25]
	s_mov_b32 m0, s39
	s_nop 0
	global_load_lds_dwordx4 v134, s[24:25]
	s_waitcnt vmcnt(8)
	s_waitcnt lgkmcnt(0)
	s_setprio 1
	s_barrier
	v_mfma_f32_16x16x32_bf16 v[62:65], v[142:145], v[182:185], v[62:65]
	v_mfma_f32_16x16x32_bf16 v[62:65], v[154:157], v[186:189], v[62:65]
	v_mfma_f32_16x16x32_bf16 v[46:49], v[142:145], v[190:193], v[46:49]
	v_mfma_f32_16x16x32_bf16 v[46:49], v[154:157], v[194:197], v[46:49]
	v_mfma_f32_16x16x32_bf16 v[30:33], v[142:145], v[206:209], v[30:33]
	v_mfma_f32_16x16x32_bf16 v[30:33], v[154:157], v[212:215], v[30:33]
	v_mfma_f32_16x16x32_bf16 v[14:17], v[142:145], v[220:223], v[14:17]
	v_mfma_f32_16x16x32_bf16 v[14:17], v[154:157], v[224:227], v[14:17]
	v_mfma_f32_16x16x32_bf16 v[58:61], v[158:161], v[182:185], v[58:61]
	v_mfma_f32_16x16x32_bf16 v[58:61], v[162:165], v[186:189], v[58:61]
	v_mfma_f32_16x16x32_bf16 v[42:45], v[158:161], v[190:193], v[42:45]
	v_mfma_f32_16x16x32_bf16 v[42:45], v[162:165], v[194:197], v[42:45]
	v_mfma_f32_16x16x32_bf16 v[26:29], v[158:161], v[206:209], v[26:29]
	v_mfma_f32_16x16x32_bf16 v[26:29], v[162:165], v[212:215], v[26:29]
	v_mfma_f32_16x16x32_bf16 v[10:13], v[158:161], v[220:223], v[10:13]
	v_mfma_f32_16x16x32_bf16 v[10:13], v[162:165], v[224:227], v[10:13]
	s_setprio 0
	s_setprio 1
	v_mfma_f32_16x16x32_bf16 v[54:57], v[166:169], v[182:185], v[54:57]
	v_mfma_f32_16x16x32_bf16 v[54:57], v[170:173], v[186:189], v[54:57]
	v_mfma_f32_16x16x32_bf16 v[38:41], v[166:169], v[190:193], v[38:41]
	v_mfma_f32_16x16x32_bf16 v[38:41], v[170:173], v[194:197], v[38:41]
	v_mfma_f32_16x16x32_bf16 v[22:25], v[166:169], v[206:209], v[22:25]
	v_mfma_f32_16x16x32_bf16 v[22:25], v[170:173], v[212:215], v[22:25]
	v_mfma_f32_16x16x32_bf16 v[6:9], v[166:169], v[220:223], v[6:9]
	v_mfma_f32_16x16x32_bf16 v[6:9], v[170:173], v[224:227], v[6:9]
	v_mfma_f32_16x16x32_bf16 v[50:53], v[174:177], v[182:185], v[50:53]
	v_mfma_f32_16x16x32_bf16 v[50:53], v[178:181], v[186:189], v[50:53]
	v_mfma_f32_16x16x32_bf16 v[34:37], v[174:177], v[190:193], v[34:37]
	v_mfma_f32_16x16x32_bf16 v[34:37], v[178:181], v[194:197], v[34:37]
	v_mfma_f32_16x16x32_bf16 v[18:21], v[174:177], v[206:209], v[18:21]
	v_mfma_f32_16x16x32_bf16 v[18:21], v[178:181], v[212:215], v[18:21]
	v_mfma_f32_16x16x32_bf16 v[2:5], v[174:177], v[220:223], v[2:5]
	v_mfma_f32_16x16x32_bf16 v[2:5], v[178:181], v[224:227], v[2:5]
	s_barrier
	s_setprio 0
	s_add_i32 s46, s46, 2
	s_add_u32 s44, s44, 0x20000
	s_addc_u32 s45, s45, 0
	s_add_u32 s22, s22, 0x200000
	s_addc_u32 s23, s23, 0
	s_cmp_gt_u32 s46, 61
	s_cbranch_scc0 .LBB0_1691
	s_lshl_b32 s7, s10, 8
	v_mov_b32_e32 v144, v147
	s_add_i32 s7, s7, s36
	v_cndmask_b32_e64 v145, 0, 1, s[2:3]
	v_and_or_b32 v142, v144, 15, s7
	v_ashrrev_i32_e32 v143, 31, v142
	v_mov_b32_e32 v146, 0x3e0293ee
	v_cmp_ne_u32_e64 s[10:11], 1, v145
	s_andn2_b64 vcc, exec, s[2:3]
	v_mov_b32_e32 v148, 0x3e0293ee
	s_cbranch_vccnz .LBB0_1694
	v_readlane_b32 s22, v245, 16
	v_readlane_b32 s23, v245, 17
	s_nop 1
	v_lshl_add_u64 v[154:155], v[142:143], 2, s[22:23]
	global_load_dword v145, v[154:155], off
	s_waitcnt vmcnt(0)
	v_mul_f32_e32 v148, 0x3e0293ee, v145

.LBB0_1718:
	ds_read_b128 v[152:155], v147
	ds_read_b128 v[156:159], v147 offset:1024
	ds_read_b128 v[160:163], v147 offset:2048
	ds_read_b128 v[164:167], v147 offset:3072
	s_add_u32 s18, s16, 0x4000
	s_addc_u32 s19, s17, 0
	s_cmp_eq_u32 s50, 60
	s_cselect_b32 s22, s14, s18
	s_cselect_b32 s23, s15, s19
	s_cselect_b32 s20, s47, s48
	s_cselect_b32 s21, s46, s49
	s_add_u32 s18, s22, 0x8000
	s_addc_u32 s19, s23, 0
	s_mov_b32 m0, s31
	ds_read_b128 v[184:187], v149
	ds_read_b128 v[188:191], v149 offset:1024
	ds_read_b128 v[192:195], v149 offset:2048
	ds_read_b128 v[196:199], v149 offset:3072
	ds_read_b128 v[206:209], v149 offset:4096
	ds_read_b128 v[212:215], v149 offset:5120
	ds_read_b128 v[220:223], v149 offset:6144
	ds_read_b128 v[224:227], v149 offset:7168
	global_load_lds_dwordx4 v140, s[16:17]
	s_mov_b32 m0, s33
	s_nop 0
	global_load_lds_dwordx4 v142, s[16:17]
	ds_read_b128 v[168:171], v148
	ds_read_b128 v[172:175], v148 offset:1024
	ds_read_b128 v[176:179], v148 offset:2048
	ds_read_b128 v[180:183], v148 offset:3072
	s_waitcnt vmcnt(8)
	s_waitcnt lgkmcnt(4)
	s_setprio 1
	s_barrier
	v_mfma_f32_16x16x32_bf16 v[126:129], v[152:155], v[184:187], v[126:129]
	v_mfma_f32_16x16x32_bf16 v[126:129], v[156:159], v[188:191], v[126:129]
	v_mfma_f32_16x16x32_bf16 v[118:121], v[152:155], v[192:195], v[118:121]
	v_mfma_f32_16x16x32_bf16 v[118:121], v[156:159], v[196:199], v[118:121]
	v_mfma_f32_16x16x32_bf16 v[102:105], v[152:155], v[206:209], v[102:105]
	v_mfma_f32_16x16x32_bf16 v[102:105], v[156:159], v[212:215], v[102:105]
	v_mfma_f32_16x16x32_bf16 v[86:89], v[152:155], v[220:223], v[86:89]
	v_mfma_f32_16x16x32_bf16 v[86:89], v[156:159], v[224:227], v[86:89]
	v_mfma_f32_16x16x32_bf16 v[122:125], v[160:163], v[184:187], v[122:125]
	v_mfma_f32_16x16x32_bf16 v[122:125], v[164:167], v[188:191], v[122:125]
	v_mfma_f32_16x16x32_bf16 v[110:113], v[160:163], v[192:195], v[110:113]
	v_mfma_f32_16x16x32_bf16 v[110:113], v[164:167], v[196:199], v[110:113]
	v_mfma_f32_16x16x32_bf16 v[94:97], v[160:163], v[206:209], v[94:97]
	v_mfma_f32_16x16x32_bf16 v[94:97], v[164:167], v[212:215], v[94:97]
	v_mfma_f32_16x16x32_bf16 v[78:81], v[160:163], v[220:223], v[78:81]
	v_mfma_f32_16x16x32_bf16 v[78:81], v[164:167], v[224:227], v[78:81]
	s_setprio 0
	s_waitcnt lgkmcnt(0)
	s_setprio 1
	v_mfma_f32_16x16x32_bf16 v[114:117], v[168:171], v[184:187], v[114:117]
	v_mfma_f32_16x16x32_bf16 v[114:117], v[172:175], v[188:191], v[114:117]
	v_mfma_f32_16x16x32_bf16 v[98:101], v[168:171], v[192:195], v[98:101]
	v_mfma_f32_16x16x32_bf16 v[98:101], v[172:175], v[196:199], v[98:101]
	v_mfma_f32_16x16x32_bf16 v[82:85], v[168:171], v[206:209], v[82:85]
	v_mfma_f32_16x16x32_bf16 v[82:85], v[172:175], v[212:215], v[82:85]
	v_mfma_f32_16x16x32_bf16 v[70:73], v[168:171], v[220:223], v[70:73]
	v_mfma_f32_16x16x32_bf16 v[70:73], v[172:175], v[224:227], v[70:73]
	v_mfma_f32_16x16x32_bf16 v[106:109], v[176:179], v[184:187], v[106:109]
	v_mfma_f32_16x16x32_bf16 v[106:109], v[180:183], v[188:191], v[106:109]
	v_mfma_f32_16x16x32_bf16 v[90:93], v[176:179], v[192:195], v[90:93]
	v_mfma_f32_16x16x32_bf16 v[90:93], v[180:183], v[196:199], v[90:93]
	v_mfma_f32_16x16x32_bf16 v[74:77], v[176:179], v[206:209], v[74:77]
	v_mfma_f32_16x16x32_bf16 v[74:77], v[180:183], v[212:215], v[74:77]
	v_mfma_f32_16x16x32_bf16 v[66:69], v[176:179], v[220:223], v[66:69]
	v_mfma_f32_16x16x32_bf16 v[66:69], v[180:183], v[224:227], v[66:69]
	s_barrier
	s_setprio 0
	s_mov_b32 m0, s36
	s_add_u32 s52, s20, 0x4000
	ds_read_b128 v[184:187], v149 offset:16384
	ds_read_b128 v[188:191], v149 offset:17408
	ds_read_b128 v[192:195], v149 offset:18432
	ds_read_b128 v[196:199], v149 offset:19456
	ds_read_b128 v[206:209], v149 offset:20480
	ds_read_b128 v[212:215], v149 offset:21504
	ds_read_b128 v[220:223], v149 offset:22528
	ds_read_b128 v[224:227], v149 offset:23552
	global_load_lds_dwordx4 v134, s[20:21]
	s_mov_b32 m0, s37
	s_addc_u32 s53, s21, 0
	global_load_lds_dwordx4 v130, s[20:21]
	s_mov_b32 m0, s38
	s_nop 0
	global_load_lds_dwordx4 v134, s[52:53]
	s_mov_b32 m0, s39
	s_nop 0
	global_load_lds_dwordx4 v130, s[52:53]
	s_mov_b32 m0, s1
	s_nop 0
	global_load_lds_dwordx4 v136, s[22:23]
	s_mov_b32 m0, s24
	s_nop 0
	global_load_lds_dwordx4 v132, s[22:23]
	s_waitcnt vmcnt(8)
	s_waitcnt lgkmcnt(0)
	s_setprio 1
	s_barrier
	v_mfma_f32_16x16x32_bf16 v[62:65], v[152:155], v[184:187], v[62:65]
	v_mfma_f32_16x16x32_bf16 v[62:65], v[156:159], v[188:191], v[62:65]
	v_mfma_f32_16x16x32_bf16 v[54:57], v[152:155], v[192:195], v[54:57]
	v_mfma_f32_16x16x32_bf16 v[54:57], v[156:159], v[196:199], v[54:57]
	v_mfma_f32_16x16x32_bf16 v[38:41], v[152:155], v[206:209], v[38:41]
	v_mfma_f32_16x16x32_bf16 v[38:41], v[156:159], v[212:215], v[38:41]
	v_mfma_f32_16x16x32_bf16 v[22:25], v[152:155], v[220:223], v[22:25]
	v_mfma_f32_16x16x32_bf16 v[22:25], v[156:159], v[224:227], v[22:25]
	v_mfma_f32_16x16x32_bf16 v[58:61], v[160:163], v[184:187], v[58:61]
	v_mfma_f32_16x16x32_bf16 v[58:61], v[164:167], v[188:191], v[58:61]
	v_mfma_f32_16x16x32_bf16 v[46:49], v[160:163], v[192:195], v[46:49]
	v_mfma_f32_16x16x32_bf16 v[46:49], v[164:167], v[196:199], v[46:49]
	v_mfma_f32_16x16x32_bf16 v[30:33], v[160:163], v[206:209], v[30:33]
	v_mfma_f32_16x16x32_bf16 v[30:33], v[164:167], v[212:215], v[30:33]
	v_mfma_f32_16x16x32_bf16 v[14:17], v[160:163], v[220:223], v[14:17]
	v_mfma_f32_16x16x32_bf16 v[14:17], v[164:167], v[224:227], v[14:17]
	s_setprio 0
	s_setprio 1
	v_mfma_f32_16x16x32_bf16 v[50:53], v[168:171], v[184:187], v[50:53]
	v_mfma_f32_16x16x32_bf16 v[50:53], v[172:175], v[188:191], v[50:53]
	v_mfma_f32_16x16x32_bf16 v[34:37], v[168:171], v[192:195], v[34:37]
	v_mfma_f32_16x16x32_bf16 v[34:37], v[172:175], v[196:199], v[34:37]
	v_mfma_f32_16x16x32_bf16 v[18:21], v[168:171], v[206:209], v[18:21]
	v_mfma_f32_16x16x32_bf16 v[18:21], v[172:175], v[212:215], v[18:21]
	v_mfma_f32_16x16x32_bf16 v[6:9], v[168:171], v[220:223], v[6:9]
	v_mfma_f32_16x16x32_bf16 v[6:9], v[172:175], v[224:227], v[6:9]
	v_mfma_f32_16x16x32_bf16 v[42:45], v[176:179], v[184:187], v[42:45]
	v_mfma_f32_16x16x32_bf16 v[42:45], v[180:183], v[188:191], v[42:45]
	v_mfma_f32_16x16x32_bf16 v[26:29], v[176:179], v[192:195], v[26:29]
	v_mfma_f32_16x16x32_bf16 v[26:29], v[180:183], v[196:199], v[26:29]
	v_mfma_f32_16x16x32_bf16 v[10:13], v[176:179], v[206:209], v[10:13]
	v_mfma_f32_16x16x32_bf16 v[10:13], v[180:183], v[212:215], v[10:13]
	v_mfma_f32_16x16x32_bf16 v[2:5], v[176:179], v[220:223], v[2:5]
	v_mfma_f32_16x16x32_bf16 v[2:5], v[180:183], v[224:227], v[2:5]
	s_barrier
	s_setprio 0
	ds_read_b128 v[152:155], v150
	ds_read_b128 v[156:159], v150 offset:1024
	ds_read_b128 v[160:163], v150 offset:2048
	ds_read_b128 v[164:167], v150 offset:3072
	s_add_u32 s22, s22, 0x4000
	s_addc_u32 s23, s23, 0
	s_mov_b32 m0, s25
	ds_read_b128 v[184:187], v149 offset:32768
	ds_read_b128 v[188:191], v149 offset:33792
	ds_read_b128 v[192:195], v149 offset:34816
	ds_read_b128 v[196:199], v149 offset:35840
	ds_read_b128 v[206:209], v149 offset:36864
	ds_read_b128 v[212:215], v149 offset:37888
	ds_read_b128 v[220:223], v149 offset:38912
	ds_read_b128 v[224:227], v149 offset:39936
	global_load_lds_dwordx4 v136, s[22:23]
	s_mov_b32 m0, s26
	s_nop 0
	global_load_lds_dwordx4 v132, s[22:23]
	ds_read_b128 v[168:171], v151
	ds_read_b128 v[172:175], v151 offset:1024
	ds_read_b128 v[176:179], v151 offset:2048
	ds_read_b128 v[180:183], v151 offset:3072
	s_waitcnt vmcnt(8)
	s_waitcnt lgkmcnt(4)
	s_setprio 1
	s_barrier
	v_mfma_f32_16x16x32_bf16 v[126:129], v[152:155], v[184:187], v[126:129]
	v_mfma_f32_16x16x32_bf16 v[126:129], v[156:159], v[188:191], v[126:129]
	v_mfma_f32_16x16x32_bf16 v[118:121], v[152:155], v[192:195], v[118:121]
	v_mfma_f32_16x16x32_bf16 v[118:121], v[156:159], v[196:199], v[118:121]
	v_mfma_f32_16x16x32_bf16 v[102:105], v[152:155], v[206:209], v[102:105]
	v_mfma_f32_16x16x32_bf16 v[102:105], v[156:159], v[212:215], v[102:105]
	v_mfma_f32_16x16x32_bf16 v[86:89], v[152:155], v[220:223], v[86:89]
	v_mfma_f32_16x16x32_bf16 v[86:89], v[156:159], v[224:227], v[86:89]
	v_mfma_f32_16x16x32_bf16 v[122:125], v[160:163], v[184:187], v[122:125]
	v_mfma_f32_16x16x32_bf16 v[122:125], v[164:167], v[188:191], v[122:125]
	v_mfma_f32_16x16x32_bf16 v[110:113], v[160:163], v[192:195], v[110:113]
	v_mfma_f32_16x16x32_bf16 v[110:113], v[164:167], v[196:199], v[110:113]
	v_mfma_f32_16x16x32_bf16 v[94:97], v[160:163], v[206:209], v[94:97]
	v_mfma_f32_16x16x32_bf16 v[94:97], v[164:167], v[212:215], v[94:97]
	v_mfma_f32_16x16x32_bf16 v[78:81], v[160:163], v[220:223], v[78:81]
	v_mfma_f32_16x16x32_bf16 v[78:81], v[164:167], v[224:227], v[78:81]
	s_setprio 0
	s_waitcnt lgkmcnt(0)
	s_setprio 1
	v_mfma_f32_16x16x32_bf16 v[114:117], v[168:171], v[184:187], v[114:117]
	v_mfma_f32_16x16x32_bf16 v[114:117], v[172:175], v[188:191], v[114:117]
	v_mfma_f32_16x16x32_bf16 v[98:101], v[168:171], v[192:195], v[98:101]
	v_mfma_f32_16x16x32_bf16 v[98:101], v[172:175], v[196:199], v[98:101]
	v_mfma_f32_16x16x32_bf16 v[82:85], v[168:171], v[206:209], v[82:85]
	v_mfma_f32_16x16x32_bf16 v[82:85], v[172:175], v[212:215], v[82:85]
	v_mfma_f32_16x16x32_bf16 v[70:73], v[168:171], v[220:223], v[70:73]
	v_mfma_f32_16x16x32_bf16 v[70:73], v[172:175], v[224:227], v[70:73]
	v_mfma_f32_16x16x32_bf16 v[106:109], v[176:179], v[184:187], v[106:109]
	v_mfma_f32_16x16x32_bf16 v[106:109], v[180:183], v[188:191], v[106:109]
	v_mfma_f32_16x16x32_bf16 v[90:93], v[176:179], v[192:195], v[90:93]
	v_mfma_f32_16x16x32_bf16 v[90:93], v[180:183], v[196:199], v[90:93]
	v_mfma_f32_16x16x32_bf16 v[74:77], v[176:179], v[206:209], v[74:77]
	v_mfma_f32_16x16x32_bf16 v[74:77], v[180:183], v[212:215], v[74:77]
	v_mfma_f32_16x16x32_bf16 v[66:69], v[176:179], v[220:223], v[66:69]
	v_mfma_f32_16x16x32_bf16 v[66:69], v[180:183], v[224:227], v[66:69]
	s_barrier
	s_setprio 0
	s_add_u32 s22, s20, 0x20000
	s_addc_u32 s23, s21, 0
	s_mov_b32 m0, s40
	s_add_u32 s20, s20, 0x24000
	ds_read_b128 v[184:187], v149 offset:49152
	ds_read_b128 v[188:191], v149 offset:50176
	ds_read_b128 v[192:195], v149 offset:51200
	ds_read_b128 v[196:199], v149 offset:52224
	ds_read_b128 v[206:209], v149 offset:53248
	ds_read_b128 v[212:215], v149 offset:54272
	ds_read_b128 v[220:223], v149 offset:55296
	ds_read_b128 v[224:227], v149 offset:56320
	global_load_lds_dwordx4 v134, s[22:23]
	s_mov_b32 m0, s41
	s_addc_u32 s21, s21, 0
	global_load_lds_dwordx4 v130, s[22:23]
	s_mov_b32 m0, s42
	s_nop 0
	global_load_lds_dwordx4 v134, s[20:21]
	s_mov_b32 m0, s43
	s_nop 0
	global_load_lds_dwordx4 v130, s[20:21]
	s_mov_b32 m0, s29
	s_nop 0
	global_load_lds_dwordx4 v136, s[18:19]
	s_mov_b32 m0, s30
	s_nop 0
	global_load_lds_dwordx4 v132, s[18:19]
	s_waitcnt vmcnt(8)
	s_waitcnt lgkmcnt(0)
	s_setprio 1
	s_barrier
	v_mfma_f32_16x16x32_bf16 v[62:65], v[152:155], v[184:187], v[62:65]
	v_mfma_f32_16x16x32_bf16 v[62:65], v[156:159], v[188:191], v[62:65]
	v_mfma_f32_16x16x32_bf16 v[54:57], v[152:155], v[192:195], v[54:57]
	v_mfma_f32_16x16x32_bf16 v[54:57], v[156:159], v[196:199], v[54:57]
	v_mfma_f32_16x16x32_bf16 v[38:41], v[152:155], v[206:209], v[38:41]
	v_mfma_f32_16x16x32_bf16 v[38:41], v[156:159], v[212:215], v[38:41]
	v_mfma_f32_16x16x32_bf16 v[22:25], v[152:155], v[220:223], v[22:25]
	v_mfma_f32_16x16x32_bf16 v[22:25], v[156:159], v[224:227], v[22:25]
	v_mfma_f32_16x16x32_bf16 v[58:61], v[160:163], v[184:187], v[58:61]
	v_mfma_f32_16x16x32_bf16 v[58:61], v[164:167], v[188:191], v[58:61]
	v_mfma_f32_16x16x32_bf16 v[46:49], v[160:163], v[192:195], v[46:49]
	v_mfma_f32_16x16x32_bf16 v[46:49], v[164:167], v[196:199], v[46:49]
	v_mfma_f32_16x16x32_bf16 v[30:33], v[160:163], v[206:209], v[30:33]
	v_mfma_f32_16x16x32_bf16 v[30:33], v[164:167], v[212:215], v[30:33]
	v_mfma_f32_16x16x32_bf16 v[14:17], v[160:163], v[220:223], v[14:17]
	v_mfma_f32_16x16x32_bf16 v[14:17], v[164:167], v[224:227], v[14:17]
	s_setprio 0
	s_setprio 1
	v_mfma_f32_16x16x32_bf16 v[50:53], v[168:171], v[184:187], v[50:53]
	v_mfma_f32_16x16x32_bf16 v[50:53], v[172:175], v[188:191], v[50:53]
	v_mfma_f32_16x16x32_bf16 v[34:37], v[168:171], v[192:195], v[34:37]
	v_mfma_f32_16x16x32_bf16 v[34:37], v[172:175], v[196:199], v[34:37]
	v_mfma_f32_16x16x32_bf16 v[18:21], v[168:171], v[206:209], v[18:21]
	v_mfma_f32_16x16x32_bf16 v[18:21], v[172:175], v[212:215], v[18:21]
	v_mfma_f32_16x16x32_bf16 v[6:9], v[168:171], v[220:223], v[6:9]
	v_mfma_f32_16x16x32_bf16 v[6:9], v[172:175], v[224:227], v[6:9]
	v_mfma_f32_16x16x32_bf16 v[42:45], v[176:179], v[184:187], v[42:45]
	v_mfma_f32_16x16x32_bf16 v[42:45], v[180:183], v[188:191], v[42:45]
	v_mfma_f32_16x16x32_bf16 v[26:29], v[176:179], v[192:195], v[26:29]
	v_mfma_f32_16x16x32_bf16 v[26:29], v[180:183], v[196:199], v[26:29]
	v_mfma_f32_16x16x32_bf16 v[10:13], v[176:179], v[206:209], v[10:13]
	v_mfma_f32_16x16x32_bf16 v[10:13], v[180:183], v[212:215], v[10:13]
	v_mfma_f32_16x16x32_bf16 v[2:5], v[176:179], v[220:223], v[2:5]
	v_mfma_f32_16x16x32_bf16 v[2:5], v[180:183], v[224:227], v[2:5]
	s_barrier
	s_setprio 0
	s_add_i32 s50, s50, 2
	s_add_u32 s48, s48, 0x40000
	s_addc_u32 s49, s49, 0
	s_add_u32 s16, s16, 0x10000
	s_addc_u32 s17, s17, 0
	s_cmp_gt_u32 s50, 61
	s_cbranch_scc0 .LBB0_1718
	v_mov_b32_e32 v138, v146
	s_lshl_b32 s16, s45, 8
	v_and_or_b32 v152, v138, 15, s27
	v_lshrrev_b32_e32 v138, 1, v138
	v_and_or_b32 v138, v138, 24, s16
	v_ashrrev_i32_e32 v153, 31, v152
	v_or_b32_e32 v138, s28, v138
	v_lshlrev_b64 v[144:145], 11, v[152:153]
	v_lshl_add_u64 v[144:145], s[8:9], 0, v[144:145]
	v_lshlrev_b64 v[154:155], 1, v[138:139]
	v_lshl_add_u64 v[144:145], v[144:145], 0, v[154:155]
	v_cvt_pk_bf16_f32 v126, v126, v127
	v_cvt_pk_bf16_f32 v127, v128, v129
	v_cvt_pk_bf16_f32 v128, v122, v123
	v_cvt_pk_bf16_f32 v129, v124, v125
	global_store_dwordx4 v[144:145], v[126:129], off
	v_cvt_pk_bf16_f32 v114, v114, v115
	v_cvt_pk_bf16_f32 v115, v116, v117
	v_cvt_pk_bf16_f32 v116, v106, v107
	v_or_b32_e32 v106, 16, v152
	v_ashrrev_i32_e32 v107, 31, v106
	v_lshlrev_b64 v[106:107], 11, v[106:107]
	v_lshl_add_u64 v[106:107], s[8:9], 0, v[106:107]
	v_cvt_pk_bf16_f32 v117, v108, v109
	global_store_dwordx4 v[144:145], v[114:117], off offset:256
	s_mov_b64 s[16:17], 0x40000
	s_cmp_eq_u32 s44, 4
	v_lshl_add_u64 v[114:115], v[106:107], 0, v[154:155]
	v_cvt_pk_bf16_f32 v106, v118, v119
	v_cvt_pk_bf16_f32 v107, v120, v121
	v_cvt_pk_bf16_f32 v108, v110, v111
	v_cvt_pk_bf16_f32 v109, v112, v113
	global_store_dwordx4 v[114:115], v[106:109], off
	v_cvt_pk_bf16_f32 v98, v98, v99
	v_cvt_pk_bf16_f32 v99, v100, v101
	v_cvt_pk_bf16_f32 v100, v90, v91
	v_or_b32_e32 v90, 32, v152
	v_ashrrev_i32_e32 v91, 31, v90
	v_lshlrev_b64 v[90:91], 11, v[90:91]
	v_lshl_add_u64 v[90:91], s[8:9], 0, v[90:91]
	v_cvt_pk_bf16_f32 v101, v92, v93
	global_store_dwordx4 v[114:115], v[98:101], off offset:256
	s_mov_b32 s45, s44
	s_nop 0
	v_lshl_add_u64 v[98:99], v[90:91], 0, v[154:155]
	v_cvt_pk_bf16_f32 v90, v102, v103
	v_cvt_pk_bf16_f32 v91, v104, v105
	v_cvt_pk_bf16_f32 v92, v94, v95
	v_cvt_pk_bf16_f32 v93, v96, v97
	global_store_dwordx4 v[98:99], v[90:93], off
	v_cvt_pk_bf16_f32 v82, v82, v83
	v_cvt_pk_bf16_f32 v83, v84, v85
	v_cvt_pk_bf16_f32 v84, v74, v75
	v_or_b32_e32 v74, 48, v152
	v_ashrrev_i32_e32 v75, 31, v74
	v_lshlrev_b64 v[74:75], 11, v[74:75]
	v_lshl_add_u64 v[74:75], s[8:9], 0, v[74:75]
	v_cvt_pk_bf16_f32 v85, v76, v77
	global_store_dwordx4 v[98:99], v[82:85], off offset:256
	s_nop 1
	v_lshl_add_u64 v[82:83], v[74:75], 0, v[154:155]
	v_cvt_pk_bf16_f32 v74, v86, v87
	v_cvt_pk_bf16_f32 v75, v88, v89
	v_cvt_pk_bf16_f32 v76, v78, v79
	v_cvt_pk_bf16_f32 v77, v80, v81
	global_store_dwordx4 v[82:83], v[74:77], off
	v_cvt_pk_bf16_f32 v70, v70, v71
	v_cvt_pk_bf16_f32 v71, v72, v73
	v_cvt_pk_bf16_f32 v72, v66, v67
	v_lshl_add_u64 v[66:67], v[144:145], 0, s[16:17]
	s_mov_b32 s16, 0x40000
	v_cvt_pk_bf16_f32 v73, v68, v69
	global_store_dwordx4 v[82:83], v[70:73], off offset:256
	v_cvt_pk_bf16_f32 v62, v62, v63
	v_cvt_pk_bf16_f32 v63, v64, v65
	v_cvt_pk_bf16_f32 v64, v58, v59
	v_add_co_u32_e32 v58, vcc, s16, v144
	v_cvt_pk_bf16_f32 v65, v60, v61
	s_mov_b64 s[16:17], 0x48000
	s_nop 0
	v_addc_co_u32_e32 v59, vcc, 0, v145, vcc
	global_store_dwordx4 v[58:59], v[62:65], off
	v_cvt_pk_bf16_f32 v50, v50, v51
	v_cvt_pk_bf16_f32 v51, v52, v53
	v_cvt_pk_bf16_f32 v52, v42, v43
	v_cvt_pk_bf16_f32 v53, v44, v45
	global_store_dwordx4 v[66:67], v[50:53], off offset:256
	v_cvt_pk_bf16_f32 v42, v54, v55
	v_cvt_pk_bf16_f32 v43, v56, v57
	v_cvt_pk_bf16_f32 v44, v46, v47
	v_cvt_pk_bf16_f32 v45, v48, v49
	s_nop 1
	v_lshl_add_u64 v[50:51], v[144:145], 0, s[16:17]
	s_mov_b32 s16, 0x48000
	v_add_co_u32_e32 v46, vcc, s16, v144
	s_mov_b64 s[16:17], s[10:11]
	s_nop 0
	v_addc_co_u32_e32 v47, vcc, 0, v145, vcc
	global_store_dwordx4 v[46:47], v[42:45], off
	v_cvt_pk_bf16_f32 v34, v34, v35
	v_cvt_pk_bf16_f32 v35, v36, v37
	v_cvt_pk_bf16_f32 v36, v26, v27
	v_cvt_pk_bf16_f32 v37, v28, v29
	global_store_dwordx4 v[50:51], v[34:37], off offset:256
	v_cvt_pk_bf16_f32 v26, v38, v39
	v_cvt_pk_bf16_f32 v27, v40, v41
	v_cvt_pk_bf16_f32 v28, v30, v31
	v_add_co_u32_e32 v30, vcc, s34, v144
	s_nop 0
	v_lshl_add_u64 v[34:35], v[144:145], 0, s[4:5]
	v_addc_co_u32_e32 v31, vcc, 0, v145, vcc
	v_cvt_pk_bf16_f32 v29, v32, v33
	global_store_dwordx4 v[30:31], v[26:29], off
	v_cvt_pk_bf16_f32 v18, v18, v19
	v_cvt_pk_bf16_f32 v19, v20, v21
	v_cvt_pk_bf16_f32 v20, v10, v11
	v_cvt_pk_bf16_f32 v21, v12, v13
	global_store_dwordx4 v[34:35], v[18:21], off offset:256
	v_cvt_pk_bf16_f32 v10, v22, v23
	v_cvt_pk_bf16_f32 v11, v24, v25
	v_cvt_pk_bf16_f32 v12, v14, v15
	v_add_co_u32_e32 v14, vcc, s35, v144
	s_nop 0
	v_lshl_add_u64 v[18:19], v[144:145], 0, s[6:7]
	v_addc_co_u32_e32 v15, vcc, 0, v145, vcc
	v_cvt_pk_bf16_f32 v13, v16, v17
	global_store_dwordx4 v[14:15], v[10:13], off
	v_cvt_pk_bf16_f32 v6, v6, v7
	v_cvt_pk_bf16_f32 v7, v8, v9
	v_cvt_pk_bf16_f32 v8, v2, v3
	v_cvt_pk_bf16_f32 v9, v4, v5
	global_store_dwordx4 v[18:19], v[6:9], off offset:256
	s_cbranch_scc0 .LBB0_1717
	s_waitcnt vmcnt(0)
	s_cmpk_gt_u32 s0, 0xff
	s_cbranch_scc1 .LBB0_1722
	s_barrier

.LBB0_2185:
	ds_read_b128 v[146:149], v152
	ds_read_b128 v[156:159], v152 offset:1024
	ds_read_b128 v[160:163], v152 offset:2048
	ds_read_b128 v[164:167], v152 offset:3072
	s_add_u32 s22, s20, 0xfc000
	s_addc_u32 s23, s21, 0
	s_cmp_eq_u32 s44, 4
	s_cselect_b32 s26, s15, s22
	s_cselect_b32 s27, s5, s23
	s_cselect_b32 s24, s41, s42
	s_cselect_b32 s25, s13, s43
	s_add_u32 s22, s26, 0x100000
	s_addc_u32 s23, s27, 0
	s_add_i32 m0, s1, 0xc000
	ds_read_b128 v[184:187], v154
	ds_read_b128 v[188:191], v154 offset:1024
	ds_read_b128 v[192:195], v154 offset:2048
	ds_read_b128 v[196:199], v154 offset:3072
	ds_read_b128 v[206:209], v154 offset:4096
	ds_read_b128 v[212:215], v154 offset:5120
	ds_read_b128 v[220:223], v154 offset:6144
	ds_read_b128 v[224:227], v154 offset:7168
	global_load_lds_dwordx4 v138, s[20:21]
	s_add_i32 m0, s1, 0xe000
	s_nop 0
	global_load_lds_dwordx4 v140, s[20:21]
	ds_read_b128 v[168:171], v153
	ds_read_b128 v[172:175], v153 offset:1024
	ds_read_b128 v[176:179], v153 offset:2048
	ds_read_b128 v[180:183], v153 offset:3072
	s_waitcnt vmcnt(8)
	s_waitcnt lgkmcnt(4)
	s_setprio 1
	s_barrier
	v_mfma_f32_16x16x32_bf16 v[126:129], v[146:149], v[184:187], v[126:129]
	v_mfma_f32_16x16x32_bf16 v[126:129], v[156:159], v[188:191], v[126:129]
	v_mfma_f32_16x16x32_bf16 v[110:113], v[146:149], v[192:195], v[110:113]
	v_mfma_f32_16x16x32_bf16 v[110:113], v[156:159], v[196:199], v[110:113]
	v_mfma_f32_16x16x32_bf16 v[94:97], v[146:149], v[206:209], v[94:97]
	v_mfma_f32_16x16x32_bf16 v[94:97], v[156:159], v[212:215], v[94:97]
	v_mfma_f32_16x16x32_bf16 v[78:81], v[146:149], v[220:223], v[78:81]
	v_mfma_f32_16x16x32_bf16 v[78:81], v[156:159], v[224:227], v[78:81]
	v_mfma_f32_16x16x32_bf16 v[122:125], v[160:163], v[184:187], v[122:125]
	v_mfma_f32_16x16x32_bf16 v[122:125], v[164:167], v[188:191], v[122:125]
	v_mfma_f32_16x16x32_bf16 v[106:109], v[160:163], v[192:195], v[106:109]
	v_mfma_f32_16x16x32_bf16 v[106:109], v[164:167], v[196:199], v[106:109]
	v_mfma_f32_16x16x32_bf16 v[90:93], v[160:163], v[206:209], v[90:93]
	v_mfma_f32_16x16x32_bf16 v[90:93], v[164:167], v[212:215], v[90:93]
	v_mfma_f32_16x16x32_bf16 v[74:77], v[160:163], v[220:223], v[74:77]
	v_mfma_f32_16x16x32_bf16 v[74:77], v[164:167], v[224:227], v[74:77]
	s_setprio 0
	s_waitcnt lgkmcnt(0)
	s_setprio 1
	v_mfma_f32_16x16x32_bf16 v[118:121], v[168:171], v[184:187], v[118:121]
	v_mfma_f32_16x16x32_bf16 v[118:121], v[172:175], v[188:191], v[118:121]
	v_mfma_f32_16x16x32_bf16 v[102:105], v[168:171], v[192:195], v[102:105]
	v_mfma_f32_16x16x32_bf16 v[102:105], v[172:175], v[196:199], v[102:105]
	v_mfma_f32_16x16x32_bf16 v[86:89], v[168:171], v[206:209], v[86:89]
	v_mfma_f32_16x16x32_bf16 v[86:89], v[172:175], v[212:215], v[86:89]
	v_mfma_f32_16x16x32_bf16 v[70:73], v[168:171], v[220:223], v[70:73]
	v_mfma_f32_16x16x32_bf16 v[70:73], v[172:175], v[224:227], v[70:73]
	v_mfma_f32_16x16x32_bf16 v[114:117], v[176:179], v[184:187], v[114:117]
	v_mfma_f32_16x16x32_bf16 v[114:117], v[180:183], v[188:191], v[114:117]
	v_mfma_f32_16x16x32_bf16 v[98:101], v[176:179], v[192:195], v[98:101]
	v_mfma_f32_16x16x32_bf16 v[98:101], v[180:183], v[196:199], v[98:101]
	v_mfma_f32_16x16x32_bf16 v[82:85], v[176:179], v[206:209], v[82:85]
	v_mfma_f32_16x16x32_bf16 v[82:85], v[180:183], v[212:215], v[82:85]
	v_mfma_f32_16x16x32_bf16 v[66:69], v[176:179], v[220:223], v[66:69]
	v_mfma_f32_16x16x32_bf16 v[66:69], v[180:183], v[224:227], v[66:69]
	s_barrier
	s_setprio 0
	s_add_i32 s45, s38, s0
	s_mov_b32 m0, s45
	ds_read_b128 v[184:187], v154 offset:16384
	ds_read_b128 v[188:191], v154 offset:17408
	ds_read_b128 v[192:195], v154 offset:18432
	ds_read_b128 v[196:199], v154 offset:19456
	ds_read_b128 v[206:209], v154 offset:20480
	ds_read_b128 v[212:215], v154 offset:21504
	ds_read_b128 v[220:223], v154 offset:22528
	ds_read_b128 v[224:227], v154 offset:23552
	global_load_lds_dwordx4 v132, s[24:25]
	s_add_i32 m0, s45, 0x2000
	s_add_u32 s46, s24, 0x4000
	s_addc_u32 s47, s25, 0
	s_add_i32 s45, s39, s0
	global_load_lds_dwordx4 v136, s[24:25]
	s_mov_b32 m0, s45
	s_nop 0
	global_load_lds_dwordx4 v132, s[46:47]
	s_add_i32 m0, s45, 0x2000
	s_nop 0
	global_load_lds_dwordx4 v136, s[46:47]
	s_mov_b32 m0, s1
	s_nop 0
	global_load_lds_dwordx4 v130, s[26:27]
	s_mov_b32 m0, s28
	s_nop 0
	global_load_lds_dwordx4 v134, s[26:27]
	s_waitcnt vmcnt(8)
	s_waitcnt lgkmcnt(0)
	s_setprio 1
	s_barrier
	v_mfma_f32_16x16x32_bf16 v[62:65], v[146:149], v[184:187], v[62:65]
	v_mfma_f32_16x16x32_bf16 v[62:65], v[156:159], v[188:191], v[62:65]
	v_mfma_f32_16x16x32_bf16 v[46:49], v[146:149], v[192:195], v[46:49]
	v_mfma_f32_16x16x32_bf16 v[46:49], v[156:159], v[196:199], v[46:49]
	v_mfma_f32_16x16x32_bf16 v[30:33], v[146:149], v[206:209], v[30:33]
	v_mfma_f32_16x16x32_bf16 v[30:33], v[156:159], v[212:215], v[30:33]
	v_mfma_f32_16x16x32_bf16 v[14:17], v[146:149], v[220:223], v[14:17]
	v_mfma_f32_16x16x32_bf16 v[14:17], v[156:159], v[224:227], v[14:17]
	v_mfma_f32_16x16x32_bf16 v[58:61], v[160:163], v[184:187], v[58:61]
	v_mfma_f32_16x16x32_bf16 v[58:61], v[164:167], v[188:191], v[58:61]
	v_mfma_f32_16x16x32_bf16 v[42:45], v[160:163], v[192:195], v[42:45]
	v_mfma_f32_16x16x32_bf16 v[42:45], v[164:167], v[196:199], v[42:45]
	v_mfma_f32_16x16x32_bf16 v[26:29], v[160:163], v[206:209], v[26:29]
	v_mfma_f32_16x16x32_bf16 v[26:29], v[164:167], v[212:215], v[26:29]
	v_mfma_f32_16x16x32_bf16 v[10:13], v[160:163], v[220:223], v[10:13]
	v_mfma_f32_16x16x32_bf16 v[10:13], v[164:167], v[224:227], v[10:13]
	s_setprio 0
	s_setprio 1
	v_mfma_f32_16x16x32_bf16 v[54:57], v[168:171], v[184:187], v[54:57]
	v_mfma_f32_16x16x32_bf16 v[54:57], v[172:175], v[188:191], v[54:57]
	v_mfma_f32_16x16x32_bf16 v[38:41], v[168:171], v[192:195], v[38:41]
	v_mfma_f32_16x16x32_bf16 v[38:41], v[172:175], v[196:199], v[38:41]
	v_mfma_f32_16x16x32_bf16 v[22:25], v[168:171], v[206:209], v[22:25]
	v_mfma_f32_16x16x32_bf16 v[22:25], v[172:175], v[212:215], v[22:25]
	v_mfma_f32_16x16x32_bf16 v[6:9], v[168:171], v[220:223], v[6:9]
	v_mfma_f32_16x16x32_bf16 v[6:9], v[172:175], v[224:227], v[6:9]
	v_mfma_f32_16x16x32_bf16 v[50:53], v[176:179], v[184:187], v[50:53]
	v_mfma_f32_16x16x32_bf16 v[50:53], v[180:183], v[188:191], v[50:53]
	v_mfma_f32_16x16x32_bf16 v[34:37], v[176:179], v[192:195], v[34:37]
	v_mfma_f32_16x16x32_bf16 v[34:37], v[180:183], v[196:199], v[34:37]
	v_mfma_f32_16x16x32_bf16 v[18:21], v[176:179], v[206:209], v[18:21]
	v_mfma_f32_16x16x32_bf16 v[18:21], v[180:183], v[212:215], v[18:21]
	v_mfma_f32_16x16x32_bf16 v[2:5], v[176:179], v[220:223], v[2:5]
	v_mfma_f32_16x16x32_bf16 v[2:5], v[180:183], v[224:227], v[2:5]
	s_barrier
	s_setprio 0
	s_add_i32 s45, 0, 0x18000
	v_add_u32_e32 v155, s45, v151
	s_add_i32 s46, 0, 0x1c000
	ds_read_b128 v[146:149], v155
	ds_read_b128 v[156:159], v155 offset:1024
	ds_read_b128 v[160:163], v155 offset:2048
	ds_read_b128 v[164:167], v155 offset:3072
	v_add_u32_e32 v155, s46, v151
	s_add_u32 s26, s26, 0x4000
	s_addc_u32 s27, s27, 0
	s_mov_b32 m0, s29
	ds_read_b128 v[184:187], v154 offset:32768
	ds_read_b128 v[188:191], v154 offset:33792
	ds_read_b128 v[192:195], v154 offset:34816
	ds_read_b128 v[196:199], v154 offset:35840
	ds_read_b128 v[206:209], v154 offset:36864
	ds_read_b128 v[212:215], v154 offset:37888
	ds_read_b128 v[220:223], v154 offset:38912
	ds_read_b128 v[224:227], v154 offset:39936
	global_load_lds_dwordx4 v130, s[26:27]
	s_mov_b32 m0, s30
	s_nop 0
	global_load_lds_dwordx4 v134, s[26:27]
	ds_read_b128 v[168:171], v155
	ds_read_b128 v[172:175], v155 offset:1024
	ds_read_b128 v[176:179], v155 offset:2048
	ds_read_b128 v[180:183], v155 offset:3072
	s_waitcnt vmcnt(8)
	s_waitcnt lgkmcnt(4)
	s_setprio 1
	s_barrier
	v_mfma_f32_16x16x32_bf16 v[126:129], v[146:149], v[184:187], v[126:129]
	v_mfma_f32_16x16x32_bf16 v[126:129], v[156:159], v[188:191], v[126:129]
	v_mfma_f32_16x16x32_bf16 v[110:113], v[146:149], v[192:195], v[110:113]
	v_mfma_f32_16x16x32_bf16 v[110:113], v[156:159], v[196:199], v[110:113]
	v_mfma_f32_16x16x32_bf16 v[94:97], v[146:149], v[206:209], v[94:97]
	v_mfma_f32_16x16x32_bf16 v[94:97], v[156:159], v[212:215], v[94:97]
	v_mfma_f32_16x16x32_bf16 v[78:81], v[146:149], v[220:223], v[78:81]
	v_mfma_f32_16x16x32_bf16 v[78:81], v[156:159], v[224:227], v[78:81]
	v_mfma_f32_16x16x32_bf16 v[122:125], v[160:163], v[184:187], v[122:125]
	v_mfma_f32_16x16x32_bf16 v[122:125], v[164:167], v[188:191], v[122:125]
	v_mfma_f32_16x16x32_bf16 v[106:109], v[160:163], v[192:195], v[106:109]
	v_mfma_f32_16x16x32_bf16 v[106:109], v[164:167], v[196:199], v[106:109]
	v_mfma_f32_16x16x32_bf16 v[90:93], v[160:163], v[206:209], v[90:93]
	v_mfma_f32_16x16x32_bf16 v[90:93], v[164:167], v[212:215], v[90:93]
	v_mfma_f32_16x16x32_bf16 v[74:77], v[160:163], v[220:223], v[74:77]
	v_mfma_f32_16x16x32_bf16 v[74:77], v[164:167], v[224:227], v[74:77]
	s_setprio 0
	s_waitcnt lgkmcnt(0)
	s_setprio 1
	v_mfma_f32_16x16x32_bf16 v[118:121], v[168:171], v[184:187], v[118:121]
	v_mfma_f32_16x16x32_bf16 v[118:121], v[172:175], v[188:191], v[118:121]
	v_mfma_f32_16x16x32_bf16 v[102:105], v[168:171], v[192:195], v[102:105]
	v_mfma_f32_16x16x32_bf16 v[102:105], v[172:175], v[196:199], v[102:105]
	v_mfma_f32_16x16x32_bf16 v[86:89], v[168:171], v[206:209], v[86:89]
	v_mfma_f32_16x16x32_bf16 v[86:89], v[172:175], v[212:215], v[86:89]
	v_mfma_f32_16x16x32_bf16 v[70:73], v[168:171], v[220:223], v[70:73]
	v_mfma_f32_16x16x32_bf16 v[70:73], v[172:175], v[224:227], v[70:73]
	v_mfma_f32_16x16x32_bf16 v[114:117], v[176:179], v[184:187], v[114:117]
	v_mfma_f32_16x16x32_bf16 v[114:117], v[180:183], v[188:191], v[114:117]
	v_mfma_f32_16x16x32_bf16 v[98:101], v[176:179], v[192:195], v[98:101]
	v_mfma_f32_16x16x32_bf16 v[98:101], v[180:183], v[196:199], v[98:101]
	v_mfma_f32_16x16x32_bf16 v[82:85], v[176:179], v[206:209], v[82:85]
	v_mfma_f32_16x16x32_bf16 v[82:85], v[180:183], v[212:215], v[82:85]
	v_mfma_f32_16x16x32_bf16 v[66:69], v[176:179], v[220:223], v[66:69]
	v_mfma_f32_16x16x32_bf16 v[66:69], v[180:183], v[224:227], v[66:69]
	s_barrier
	s_setprio 0
	s_add_u32 s26, s24, 0x80000
	s_addc_u32 s27, s25, 0
	s_add_i32 s45, s45, s0
	s_mov_b32 m0, s45
	ds_read_b128 v[184:187], v154 offset:49152
	ds_read_b128 v[188:191], v154 offset:50176
	ds_read_b128 v[192:195], v154 offset:51200
	ds_read_b128 v[196:199], v154 offset:52224
	ds_read_b128 v[206:209], v154 offset:53248
	ds_read_b128 v[212:215], v154 offset:54272
	ds_read_b128 v[220:223], v154 offset:55296
	ds_read_b128 v[224:227], v154 offset:56320
	global_load_lds_dwordx4 v132, s[26:27]
	s_add_i32 m0, s45, 0x2000
	s_add_u32 s24, s24, 0x84000
	s_addc_u32 s25, s25, 0
	global_load_lds_dwordx4 v136, s[26:27]
	s_add_i32 s26, s46, s0
	s_mov_b32 m0, s26
	s_nop 0
	global_load_lds_dwordx4 v132, s[24:25]
	s_add_i32 m0, s26, 0x2000
	s_nop 0
	global_load_lds_dwordx4 v136, s[24:25]
	s_mov_b32 m0, s36
	s_nop 0
	global_load_lds_dwordx4 v130, s[22:23]
	s_mov_b32 m0, s37
	s_nop 0
	global_load_lds_dwordx4 v134, s[22:23]
	s_waitcnt vmcnt(8)
	s_waitcnt lgkmcnt(0)
	s_setprio 1
	s_barrier
	v_mfma_f32_16x16x32_bf16 v[62:65], v[146:149], v[184:187], v[62:65]
	v_mfma_f32_16x16x32_bf16 v[62:65], v[156:159], v[188:191], v[62:65]
	v_mfma_f32_16x16x32_bf16 v[46:49], v[146:149], v[192:195], v[46:49]
	v_mfma_f32_16x16x32_bf16 v[46:49], v[156:159], v[196:199], v[46:49]
	v_mfma_f32_16x16x32_bf16 v[30:33], v[146:149], v[206:209], v[30:33]
	v_mfma_f32_16x16x32_bf16 v[30:33], v[156:159], v[212:215], v[30:33]
	v_mfma_f32_16x16x32_bf16 v[14:17], v[146:149], v[220:223], v[14:17]
	v_mfma_f32_16x16x32_bf16 v[14:17], v[156:159], v[224:227], v[14:17]
	v_mfma_f32_16x16x32_bf16 v[58:61], v[160:163], v[184:187], v[58:61]
	v_mfma_f32_16x16x32_bf16 v[58:61], v[164:167], v[188:191], v[58:61]
	v_mfma_f32_16x16x32_bf16 v[42:45], v[160:163], v[192:195], v[42:45]
	v_mfma_f32_16x16x32_bf16 v[42:45], v[164:167], v[196:199], v[42:45]
	v_mfma_f32_16x16x32_bf16 v[26:29], v[160:163], v[206:209], v[26:29]
	v_mfma_f32_16x16x32_bf16 v[26:29], v[164:167], v[212:215], v[26:29]
	v_mfma_f32_16x16x32_bf16 v[10:13], v[160:163], v[220:223], v[10:13]
	v_mfma_f32_16x16x32_bf16 v[10:13], v[164:167], v[224:227], v[10:13]
	s_setprio 0
	s_setprio 1
	v_mfma_f32_16x16x32_bf16 v[54:57], v[168:171], v[184:187], v[54:57]
	v_mfma_f32_16x16x32_bf16 v[54:57], v[172:175], v[188:191], v[54:57]
	v_mfma_f32_16x16x32_bf16 v[38:41], v[168:171], v[192:195], v[38:41]
	v_mfma_f32_16x16x32_bf16 v[38:41], v[172:175], v[196:199], v[38:41]
	v_mfma_f32_16x16x32_bf16 v[22:25], v[168:171], v[206:209], v[22:25]
	v_mfma_f32_16x16x32_bf16 v[22:25], v[172:175], v[212:215], v[22:25]
	v_mfma_f32_16x16x32_bf16 v[6:9], v[168:171], v[220:223], v[6:9]
	v_mfma_f32_16x16x32_bf16 v[6:9], v[172:175], v[224:227], v[6:9]
	v_mfma_f32_16x16x32_bf16 v[50:53], v[176:179], v[184:187], v[50:53]
	v_mfma_f32_16x16x32_bf16 v[50:53], v[180:183], v[188:191], v[50:53]
	v_mfma_f32_16x16x32_bf16 v[34:37], v[176:179], v[192:195], v[34:37]
	v_mfma_f32_16x16x32_bf16 v[34:37], v[180:183], v[196:199], v[34:37]
	v_mfma_f32_16x16x32_bf16 v[18:21], v[176:179], v[206:209], v[18:21]
	v_mfma_f32_16x16x32_bf16 v[18:21], v[180:183], v[212:215], v[18:21]
	v_mfma_f32_16x16x32_bf16 v[2:5], v[176:179], v[220:223], v[2:5]
	v_mfma_f32_16x16x32_bf16 v[2:5], v[180:183], v[224:227], v[2:5]
	s_barrier
	s_setprio 0
	s_add_i32 s44, s44, 2
	s_add_u32 s42, s42, 0x100000
	s_addc_u32 s43, s43, 0
	s_add_u32 s20, s20, 0x200000
	s_addc_u32 s21, s21, 0
	s_cmp_gt_u32 s44, 5
	s_cbranch_scc0 .LBB0_2185
	s_and_b64 vcc, exec, s[8:9]
	s_cbranch_vccz .LBB0_2188
	s_barrier
